# v31 + code placement: every 8-byte instruction (MFMA, ds_read, LDS-DMA load) in the five GEMM K-loops starts on an 8-byte boundary (p2align 3 at loop head + 107 pad s_nop)
# speedup vs baseline: 1.0049x; 1.0026x over previous
.LBB0_288:
	s_lshl_b32 s65, s64, 19
	s_and_b64 s[18:19], s[8:9], exec
	s_cselect_b32 s18, s65, s78
	s_lshl_b32 s66, s63, 19
	s_and_b64 s[82:83], s[8:9], exec
	v_mov_b32_e32 v2, 0
	s_cselect_b32 s19, s66, s79
	s_add_i32 s78, s78, 0x40080
	s_addk_i32 s79, 0x100
	s_mov_b32 s80, -2
	v_mov_b32_e32 v3, v2
	v_mov_b32_e32 v4, v2
	v_mov_b32_e32 v5, v2
	v_mov_b32_e32 v6, v2
	v_mov_b32_e32 v7, v2
	v_mov_b32_e32 v8, v2
	v_mov_b32_e32 v9, v2
	v_mov_b32_e32 v18, v2
	v_mov_b32_e32 v19, v2
	v_mov_b32_e32 v20, v2
	v_mov_b32_e32 v21, v2
	v_mov_b32_e32 v22, v2
	v_mov_b32_e32 v23, v2
	v_mov_b32_e32 v24, v2
	v_mov_b32_e32 v25, v2
	v_mov_b32_e32 v34, v2
	v_mov_b32_e32 v35, v2
	v_mov_b32_e32 v36, v2
	v_mov_b32_e32 v37, v2
	v_mov_b32_e32 v38, v2
	v_mov_b32_e32 v39, v2
	v_mov_b32_e32 v40, v2
	v_mov_b32_e32 v41, v2
	v_mov_b32_e32 v50, v2
	v_mov_b32_e32 v51, v2
	v_mov_b32_e32 v52, v2
	v_mov_b32_e32 v53, v2
	v_mov_b32_e32 v54, v2
	v_mov_b32_e32 v55, v2
	v_mov_b32_e32 v56, v2
	v_mov_b32_e32 v57, v2
	v_mov_b32_e32 v10, v2
	v_mov_b32_e32 v11, v2
	v_mov_b32_e32 v12, v2
	v_mov_b32_e32 v13, v2
	v_mov_b32_e32 v14, v2
	v_mov_b32_e32 v15, v2
	v_mov_b32_e32 v16, v2
	v_mov_b32_e32 v17, v2
	v_mov_b32_e32 v26, v2
	v_mov_b32_e32 v27, v2
	v_mov_b32_e32 v28, v2
	v_mov_b32_e32 v29, v2
	v_mov_b32_e32 v30, v2
	v_mov_b32_e32 v31, v2
	v_mov_b32_e32 v32, v2
	v_mov_b32_e32 v33, v2
	v_mov_b32_e32 v42, v2
	v_mov_b32_e32 v43, v2
	v_mov_b32_e32 v44, v2
	v_mov_b32_e32 v45, v2
	v_mov_b32_e32 v46, v2
	v_mov_b32_e32 v47, v2
	v_mov_b32_e32 v48, v2
	v_mov_b32_e32 v49, v2
	v_mov_b32_e32 v58, v2
	v_mov_b32_e32 v59, v2
	v_mov_b32_e32 v60, v2
	v_mov_b32_e32 v61, v2
	v_mov_b32_e32 v62, v2
	v_mov_b32_e32 v63, v2
	v_mov_b32_e32 v64, v2
	v_mov_b32_e32 v65, v2
	v_mov_b32_e32 v66, v2
	v_mov_b32_e32 v67, v2
	v_mov_b32_e32 v68, v2
	v_mov_b32_e32 v69, v2
	v_mov_b32_e32 v70, v2
	v_mov_b32_e32 v71, v2
	v_mov_b32_e32 v72, v2
	v_mov_b32_e32 v73, v2
	v_mov_b32_e32 v82, v2
	v_mov_b32_e32 v83, v2
	v_mov_b32_e32 v84, v2
	v_mov_b32_e32 v85, v2
	v_mov_b32_e32 v86, v2
	v_mov_b32_e32 v87, v2
	v_mov_b32_e32 v88, v2
	v_mov_b32_e32 v89, v2
	v_mov_b32_e32 v98, v2
	v_mov_b32_e32 v99, v2
	v_mov_b32_e32 v100, v2
	v_mov_b32_e32 v101, v2
	v_mov_b32_e32 v102, v2
	v_mov_b32_e32 v103, v2
	v_mov_b32_e32 v104, v2
	v_mov_b32_e32 v105, v2
	v_mov_b32_e32 v114, v2
	v_mov_b32_e32 v115, v2
	v_mov_b32_e32 v116, v2
	v_mov_b32_e32 v117, v2
	v_mov_b32_e32 v118, v2
	v_mov_b32_e32 v119, v2
	v_mov_b32_e32 v120, v2
	v_mov_b32_e32 v121, v2
	v_mov_b32_e32 v74, v2
	v_mov_b32_e32 v75, v2
	v_mov_b32_e32 v76, v2
	v_mov_b32_e32 v77, v2
	v_mov_b32_e32 v78, v2
	v_mov_b32_e32 v79, v2
	v_mov_b32_e32 v80, v2
	v_mov_b32_e32 v81, v2
	v_mov_b32_e32 v90, v2
	v_mov_b32_e32 v91, v2
	v_mov_b32_e32 v92, v2
	v_mov_b32_e32 v93, v2
	v_mov_b32_e32 v94, v2
	v_mov_b32_e32 v95, v2
	v_mov_b32_e32 v96, v2
	v_mov_b32_e32 v97, v2
	v_mov_b32_e32 v106, v2
	v_mov_b32_e32 v107, v2
	v_mov_b32_e32 v108, v2
	v_mov_b32_e32 v109, v2
	v_mov_b32_e32 v110, v2
	v_mov_b32_e32 v111, v2
	v_mov_b32_e32 v112, v2
	v_mov_b32_e32 v113, v2
	v_mov_b32_e32 v122, v2
	v_mov_b32_e32 v123, v2
	v_mov_b32_e32 v124, v2
	v_mov_b32_e32 v125, v2
	v_mov_b32_e32 v126, v2
	v_mov_b32_e32 v127, v2
	v_mov_b32_e32 v128, v2
	v_mov_b32_e32 v129, v2
	.p2align 3
.LBB0_289:
	ds_read_b128 v[134:137], v161
	ds_read_b128 v[138:141], v161 offset:1024
	ds_read_b128 v[142:145], v161 offset:2048
	ds_read_b128 v[146:149], v161 offset:3072
	ds_read_b128 v[150:153], v162
	ds_read_b128 v[166:169], v162 offset:1024
	ds_read_b128 v[170:173], v162 offset:2048
	ds_read_b128 v[174:177], v162 offset:3072
	s_add_i32 s39, s78, 0xfffc0080
	s_cmp_eq_u32 s80, 12
	s_cselect_b32 s88, s18, s39
	s_cselect_b32 s83, s19, s79
	s_nop 0
	s_or_b32 s82, s88, 0x80
	s_mov_b32 m0, s59
	s_nop 0
	ds_read_b128 v[178:181], v163
	ds_read_b128 v[182:185], v163 offset:1024
	ds_read_b128 v[186:189], v163 offset:2048
	ds_read_b128 v[190:193], v163 offset:3072
	ds_read_b128 v[194:197], v163 offset:4096
	ds_read_b128 v[198:201], v163 offset:5120
	ds_read_b128 v[202:205], v163 offset:6144
	ds_read_b128 v[206:209], v163 offset:7168
	buffer_load_dwordx4 v1, s[28:31], s78 offen lds
	s_mov_b32 m0, s60
	s_nop 0
	buffer_load_dwordx4 v155, s[28:31], s78 offen lds
	s_waitcnt vmcnt(8)
	s_waitcnt lgkmcnt(0)
	s_barrier
	s_setprio 1
	s_waitcnt lgkmcnt(0)
	s_nop 0
	v_mfma_i32_16x16x64_i8 v[126:129], v[134:137], v[178:181], v[126:129]
	v_mfma_i32_16x16x64_i8 v[122:125], v[142:145], v[178:181], v[122:125]
	v_mfma_i32_16x16x64_i8 v[110:113], v[134:137], v[186:189], v[110:113]
	v_mfma_i32_16x16x64_i8 v[106:109], v[142:145], v[186:189], v[106:109]
	v_mfma_i32_16x16x64_i8 v[94:97], v[134:137], v[194:197], v[94:97]
	v_mfma_i32_16x16x64_i8 v[90:93], v[142:145], v[194:197], v[90:93]
	v_mfma_i32_16x16x64_i8 v[78:81], v[134:137], v[202:205], v[78:81]
	v_mfma_i32_16x16x64_i8 v[74:77], v[142:145], v[202:205], v[74:77]
	v_mfma_i32_16x16x64_i8 v[126:129], v[138:141], v[182:185], v[126:129]
	v_mfma_i32_16x16x64_i8 v[122:125], v[146:149], v[182:185], v[122:125]
	v_mfma_i32_16x16x64_i8 v[110:113], v[138:141], v[190:193], v[110:113]
	v_mfma_i32_16x16x64_i8 v[106:109], v[146:149], v[190:193], v[106:109]
	v_mfma_i32_16x16x64_i8 v[94:97], v[138:141], v[198:201], v[94:97]
	v_mfma_i32_16x16x64_i8 v[90:93], v[146:149], v[198:201], v[90:93]
	v_mfma_i32_16x16x64_i8 v[78:81], v[138:141], v[206:209], v[78:81]
	v_mfma_i32_16x16x64_i8 v[74:77], v[146:149], v[206:209], v[74:77]
	s_setprio 0
	s_setprio 1
	v_mfma_i32_16x16x64_i8 v[118:121], v[150:153], v[178:181], v[118:121]
	v_mfma_i32_16x16x64_i8 v[114:117], v[170:173], v[178:181], v[114:117]
	v_mfma_i32_16x16x64_i8 v[102:105], v[150:153], v[186:189], v[102:105]
	v_mfma_i32_16x16x64_i8 v[98:101], v[170:173], v[186:189], v[98:101]
	v_mfma_i32_16x16x64_i8 v[86:89], v[150:153], v[194:197], v[86:89]
	v_mfma_i32_16x16x64_i8 v[82:85], v[170:173], v[194:197], v[82:85]
	v_mfma_i32_16x16x64_i8 v[70:73], v[150:153], v[202:205], v[70:73]
	v_mfma_i32_16x16x64_i8 v[66:69], v[170:173], v[202:205], v[66:69]
	v_mfma_i32_16x16x64_i8 v[118:121], v[166:169], v[182:185], v[118:121]
	v_mfma_i32_16x16x64_i8 v[114:117], v[174:177], v[182:185], v[114:117]
	v_mfma_i32_16x16x64_i8 v[102:105], v[166:169], v[190:193], v[102:105]
	v_mfma_i32_16x16x64_i8 v[98:101], v[174:177], v[190:193], v[98:101]
	v_mfma_i32_16x16x64_i8 v[86:89], v[166:169], v[198:201], v[86:89]
	v_mfma_i32_16x16x64_i8 v[82:85], v[174:177], v[198:201], v[82:85]
	v_mfma_i32_16x16x64_i8 v[70:73], v[166:169], v[206:209], v[70:73]
	v_mfma_i32_16x16x64_i8 v[66:69], v[174:177], v[206:209], v[66:69]
	s_setprio 0
	s_barrier
	s_mov_b32 m0, s35
	s_mov_b32 s39, s31
	ds_read_b128 v[178:181], v163 offset:16384
	ds_read_b128 v[182:185], v163 offset:17408
	ds_read_b128 v[186:189], v163 offset:18432
	ds_read_b128 v[190:193], v163 offset:19456
	ds_read_b128 v[194:197], v163 offset:20480
	ds_read_b128 v[198:201], v163 offset:21504
	ds_read_b128 v[202:205], v163 offset:22528
	ds_read_b128 v[206:209], v163 offset:23552
	buffer_load_dwordx4 v154, s[36:39], s83 offen lds
	s_mov_b32 m0, s40
	s_nop 0
	s_add_i32 s89, s83, 0x40000
	buffer_load_dwordx4 v156, s[36:39], s83 offen lds
	s_mov_b32 m0, s41
	s_nop 0
	buffer_load_dwordx4 v154, s[36:39], s89 offen lds
	s_mov_b32 m0, s43
	s_nop 0
	buffer_load_dwordx4 v156, s[36:39], s89 offen lds
	s_mov_b32 m0, s34
	s_nop 0
	buffer_load_dwordx4 v1, s[28:31], s88 offen lds
	s_mov_b32 m0, s44
	s_nop 0
	buffer_load_dwordx4 v155, s[28:31], s88 offen lds
	s_waitcnt vmcnt(8)
	s_waitcnt lgkmcnt(0)
	s_barrier
	s_setprio 1
	s_waitcnt lgkmcnt(0)
	s_nop 0
	v_mfma_i32_16x16x64_i8 v[62:65], v[134:137], v[178:181], v[62:65]
	v_mfma_i32_16x16x64_i8 v[58:61], v[142:145], v[178:181], v[58:61]
	s_waitcnt lgkmcnt(5)
	s_nop 0
	v_mfma_i32_16x16x64_i8 v[46:49], v[134:137], v[186:189], v[46:49]
	v_mfma_i32_16x16x64_i8 v[42:45], v[142:145], v[186:189], v[42:45]
	s_waitcnt lgkmcnt(3)
	s_nop 0
	v_mfma_i32_16x16x64_i8 v[30:33], v[134:137], v[194:197], v[30:33]
	v_mfma_i32_16x16x64_i8 v[26:29], v[142:145], v[194:197], v[26:29]
	s_waitcnt lgkmcnt(1)
	s_nop 0
	v_mfma_i32_16x16x64_i8 v[14:17], v[134:137], v[202:205], v[14:17]
	v_mfma_i32_16x16x64_i8 v[10:13], v[142:145], v[202:205], v[10:13]
	v_mfma_i32_16x16x64_i8 v[62:65], v[138:141], v[182:185], v[62:65]
	v_mfma_i32_16x16x64_i8 v[58:61], v[146:149], v[182:185], v[58:61]
	v_mfma_i32_16x16x64_i8 v[46:49], v[138:141], v[190:193], v[46:49]
	v_mfma_i32_16x16x64_i8 v[42:45], v[146:149], v[190:193], v[42:45]
	v_mfma_i32_16x16x64_i8 v[30:33], v[138:141], v[198:201], v[30:33]
	v_mfma_i32_16x16x64_i8 v[26:29], v[146:149], v[198:201], v[26:29]
	s_waitcnt lgkmcnt(0)
	s_nop 0
	v_mfma_i32_16x16x64_i8 v[14:17], v[138:141], v[206:209], v[14:17]
	v_mfma_i32_16x16x64_i8 v[10:13], v[146:149], v[206:209], v[10:13]
	s_setprio 0
	s_setprio 1
	v_mfma_i32_16x16x64_i8 v[54:57], v[150:153], v[178:181], v[54:57]
	v_mfma_i32_16x16x64_i8 v[50:53], v[170:173], v[178:181], v[50:53]
	v_mfma_i32_16x16x64_i8 v[38:41], v[150:153], v[186:189], v[38:41]
	v_mfma_i32_16x16x64_i8 v[34:37], v[170:173], v[186:189], v[34:37]
	v_mfma_i32_16x16x64_i8 v[22:25], v[150:153], v[194:197], v[22:25]
	v_mfma_i32_16x16x64_i8 v[18:21], v[170:173], v[194:197], v[18:21]
	v_mfma_i32_16x16x64_i8 v[6:9], v[150:153], v[202:205], v[6:9]
	v_mfma_i32_16x16x64_i8 v[2:5], v[170:173], v[202:205], v[2:5]
	v_mfma_i32_16x16x64_i8 v[54:57], v[166:169], v[182:185], v[54:57]
	v_mfma_i32_16x16x64_i8 v[50:53], v[174:177], v[182:185], v[50:53]
	v_mfma_i32_16x16x64_i8 v[38:41], v[166:169], v[190:193], v[38:41]
	v_mfma_i32_16x16x64_i8 v[34:37], v[174:177], v[190:193], v[34:37]
	v_mfma_i32_16x16x64_i8 v[22:25], v[166:169], v[198:201], v[22:25]
	v_mfma_i32_16x16x64_i8 v[18:21], v[174:177], v[198:201], v[18:21]
	v_mfma_i32_16x16x64_i8 v[6:9], v[166:169], v[206:209], v[6:9]
	v_mfma_i32_16x16x64_i8 v[2:5], v[174:177], v[206:209], v[2:5]
	s_setprio 0
	s_barrier
	ds_read_b128 v[134:137], v164
	ds_read_b128 v[138:141], v164 offset:1024
	ds_read_b128 v[142:145], v164 offset:2048
	ds_read_b128 v[146:149], v164 offset:3072
	ds_read_b128 v[150:153], v165
	ds_read_b128 v[166:169], v165 offset:1024
	ds_read_b128 v[170:173], v165 offset:2048
	ds_read_b128 v[174:177], v165 offset:3072
	s_add_i32 s88, s88, 0x40000
	s_mov_b32 m0, s45
	s_nop 0
	ds_read_b128 v[178:181], v163 offset:32768
	ds_read_b128 v[182:185], v163 offset:33792
	ds_read_b128 v[186:189], v163 offset:34816
	ds_read_b128 v[190:193], v163 offset:35840
	ds_read_b128 v[194:197], v163 offset:36864
	ds_read_b128 v[198:201], v163 offset:37888
	ds_read_b128 v[202:205], v163 offset:38912
	ds_read_b128 v[206:209], v163 offset:39936
	buffer_load_dwordx4 v1, s[28:31], s88 offen lds
	s_mov_b32 m0, s47
	s_nop 0
	buffer_load_dwordx4 v155, s[28:31], s88 offen lds
	s_waitcnt vmcnt(8)
	s_waitcnt lgkmcnt(0)
	s_barrier
	s_setprio 1
	s_waitcnt lgkmcnt(0)
	s_nop 0
	v_mfma_i32_16x16x64_i8 v[126:129], v[134:137], v[178:181], v[126:129]
	v_mfma_i32_16x16x64_i8 v[122:125], v[142:145], v[178:181], v[122:125]
	s_waitcnt lgkmcnt(5)
	s_nop 0
	v_mfma_i32_16x16x64_i8 v[110:113], v[134:137], v[186:189], v[110:113]
	v_mfma_i32_16x16x64_i8 v[106:109], v[142:145], v[186:189], v[106:109]
	s_waitcnt lgkmcnt(3)
	s_nop 0
	v_mfma_i32_16x16x64_i8 v[94:97], v[134:137], v[194:197], v[94:97]
	v_mfma_i32_16x16x64_i8 v[90:93], v[142:145], v[194:197], v[90:93]
	s_waitcnt lgkmcnt(1)
	s_nop 0
	v_mfma_i32_16x16x64_i8 v[78:81], v[134:137], v[202:205], v[78:81]
	v_mfma_i32_16x16x64_i8 v[74:77], v[142:145], v[202:205], v[74:77]
	v_mfma_i32_16x16x64_i8 v[126:129], v[138:141], v[182:185], v[126:129]
	v_mfma_i32_16x16x64_i8 v[122:125], v[146:149], v[182:185], v[122:125]
	v_mfma_i32_16x16x64_i8 v[110:113], v[138:141], v[190:193], v[110:113]
	v_mfma_i32_16x16x64_i8 v[106:109], v[146:149], v[190:193], v[106:109]
	v_mfma_i32_16x16x64_i8 v[94:97], v[138:141], v[198:201], v[94:97]
	v_mfma_i32_16x16x64_i8 v[90:93], v[146:149], v[198:201], v[90:93]
	s_waitcnt lgkmcnt(0)
	s_nop 0
	v_mfma_i32_16x16x64_i8 v[78:81], v[138:141], v[206:209], v[78:81]
	v_mfma_i32_16x16x64_i8 v[74:77], v[146:149], v[206:209], v[74:77]
	s_setprio 0
	s_setprio 1
	v_mfma_i32_16x16x64_i8 v[118:121], v[150:153], v[178:181], v[118:121]
	v_mfma_i32_16x16x64_i8 v[114:117], v[170:173], v[178:181], v[114:117]
	v_mfma_i32_16x16x64_i8 v[102:105], v[150:153], v[186:189], v[102:105]
	v_mfma_i32_16x16x64_i8 v[98:101], v[170:173], v[186:189], v[98:101]
	v_mfma_i32_16x16x64_i8 v[86:89], v[150:153], v[194:197], v[86:89]
	v_mfma_i32_16x16x64_i8 v[82:85], v[170:173], v[194:197], v[82:85]
	v_mfma_i32_16x16x64_i8 v[70:73], v[150:153], v[202:205], v[70:73]
	v_mfma_i32_16x16x64_i8 v[66:69], v[170:173], v[202:205], v[66:69]
	v_mfma_i32_16x16x64_i8 v[118:121], v[166:169], v[182:185], v[118:121]
	v_mfma_i32_16x16x64_i8 v[114:117], v[174:177], v[182:185], v[114:117]
	v_mfma_i32_16x16x64_i8 v[102:105], v[166:169], v[190:193], v[102:105]
	v_mfma_i32_16x16x64_i8 v[98:101], v[174:177], v[190:193], v[98:101]
	v_mfma_i32_16x16x64_i8 v[86:89], v[166:169], v[198:201], v[86:89]
	v_mfma_i32_16x16x64_i8 v[82:85], v[174:177], v[198:201], v[82:85]
	v_mfma_i32_16x16x64_i8 v[70:73], v[166:169], v[206:209], v[70:73]
	v_mfma_i32_16x16x64_i8 v[66:69], v[174:177], v[206:209], v[66:69]
	s_setprio 0
	s_barrier
	s_mov_b32 m0, s48
	s_nop 0
	s_or_b32 s88, s83, 0x80
	ds_read_b128 v[178:181], v163 offset:49152
	ds_read_b128 v[182:185], v163 offset:50176
	ds_read_b128 v[186:189], v163 offset:51200
	ds_read_b128 v[190:193], v163 offset:52224
	ds_read_b128 v[194:197], v163 offset:53248
	ds_read_b128 v[198:201], v163 offset:54272
	ds_read_b128 v[202:205], v163 offset:55296
	ds_read_b128 v[206:209], v163 offset:56320
	buffer_load_dwordx4 v154, s[36:39], s88 offen lds
	s_mov_b32 m0, s49
	s_nop 0
	s_add_i32 s83, s83, 0x40080
	buffer_load_dwordx4 v156, s[36:39], s88 offen lds
	s_mov_b32 m0, s53
	s_nop 0
	buffer_load_dwordx4 v154, s[36:39], s83 offen lds
	s_mov_b32 m0, s55
	s_nop 0
	buffer_load_dwordx4 v156, s[36:39], s83 offen lds
	s_mov_b32 m0, s51
	s_nop 0
	buffer_load_dwordx4 v1, s[28:31], s82 offen lds
	s_mov_b32 m0, s52
	s_nop 0
	buffer_load_dwordx4 v155, s[28:31], s82 offen lds
	s_waitcnt vmcnt(8)
	s_waitcnt lgkmcnt(0)
	s_barrier
	s_setprio 1
	s_waitcnt lgkmcnt(0)
	s_nop 0
	v_mfma_i32_16x16x64_i8 v[62:65], v[134:137], v[178:181], v[62:65]
	v_mfma_i32_16x16x64_i8 v[58:61], v[142:145], v[178:181], v[58:61]
	s_waitcnt lgkmcnt(5)
	s_nop 0
	v_mfma_i32_16x16x64_i8 v[46:49], v[134:137], v[186:189], v[46:49]
	v_mfma_i32_16x16x64_i8 v[42:45], v[142:145], v[186:189], v[42:45]
	s_waitcnt lgkmcnt(3)
	s_nop 0
	v_mfma_i32_16x16x64_i8 v[30:33], v[134:137], v[194:197], v[30:33]
	v_mfma_i32_16x16x64_i8 v[26:29], v[142:145], v[194:197], v[26:29]
	s_waitcnt lgkmcnt(1)
	s_nop 0
	v_mfma_i32_16x16x64_i8 v[14:17], v[134:137], v[202:205], v[14:17]
	v_mfma_i32_16x16x64_i8 v[10:13], v[142:145], v[202:205], v[10:13]
	v_mfma_i32_16x16x64_i8 v[62:65], v[138:141], v[182:185], v[62:65]
	v_mfma_i32_16x16x64_i8 v[58:61], v[146:149], v[182:185], v[58:61]
	v_mfma_i32_16x16x64_i8 v[46:49], v[138:141], v[190:193], v[46:49]
	v_mfma_i32_16x16x64_i8 v[42:45], v[146:149], v[190:193], v[42:45]
	v_mfma_i32_16x16x64_i8 v[30:33], v[138:141], v[198:201], v[30:33]
	v_mfma_i32_16x16x64_i8 v[26:29], v[146:149], v[198:201], v[26:29]
	s_waitcnt lgkmcnt(0)
	s_nop 0
	v_mfma_i32_16x16x64_i8 v[14:17], v[138:141], v[206:209], v[14:17]
	v_mfma_i32_16x16x64_i8 v[10:13], v[146:149], v[206:209], v[10:13]
	s_setprio 0
	s_setprio 1
	v_mfma_i32_16x16x64_i8 v[54:57], v[150:153], v[178:181], v[54:57]
	v_mfma_i32_16x16x64_i8 v[50:53], v[170:173], v[178:181], v[50:53]
	v_mfma_i32_16x16x64_i8 v[38:41], v[150:153], v[186:189], v[38:41]
	v_mfma_i32_16x16x64_i8 v[34:37], v[170:173], v[186:189], v[34:37]
	v_mfma_i32_16x16x64_i8 v[22:25], v[150:153], v[194:197], v[22:25]
	v_mfma_i32_16x16x64_i8 v[18:21], v[170:173], v[194:197], v[18:21]
	v_mfma_i32_16x16x64_i8 v[6:9], v[150:153], v[202:205], v[6:9]
	v_mfma_i32_16x16x64_i8 v[2:5], v[170:173], v[202:205], v[2:5]
	v_mfma_i32_16x16x64_i8 v[54:57], v[166:169], v[182:185], v[54:57]
	v_mfma_i32_16x16x64_i8 v[50:53], v[174:177], v[182:185], v[50:53]
	v_mfma_i32_16x16x64_i8 v[38:41], v[166:169], v[190:193], v[38:41]
	v_mfma_i32_16x16x64_i8 v[34:37], v[174:177], v[190:193], v[34:37]
	v_mfma_i32_16x16x64_i8 v[22:25], v[166:169], v[198:201], v[22:25]
	v_mfma_i32_16x16x64_i8 v[18:21], v[174:177], v[198:201], v[18:21]
	v_mfma_i32_16x16x64_i8 v[6:9], v[166:169], v[206:209], v[6:9]
	v_mfma_i32_16x16x64_i8 v[2:5], v[174:177], v[206:209], v[2:5]
	s_setprio 0
	s_barrier
	s_add_i32 s80, s80, 2
	s_addk_i32 s78, 0x100
	s_addk_i32 s79, 0x100
	s_cmp_gt_u32 s80, 13
	s_cbranch_scc0 .LBB0_289
	s_and_b64 vcc, exec, s[16:17]
	s_cbranch_vccz .LBB0_292
	s_barrier

.LBB0_365:
	v_and_b32_e32 v219, 15, v210
	v_and_b32_e32 v2, 48, v210
	v_lshlrev_b32_e32 v3, 2, v210
	s_and_b32 s95, s12, 3
	s_lshl_b32 s21, s57, 13
	v_lshl_or_b32 v2, v219, 6, v2
	v_and_b32_e32 v3, 32, v3
	v_bitop3_b32 v4, v2, s21, v3 bitop3:0xde
	s_lshl_b32 s21, s95, 12
	v_bitop3_b32 v3, s21, v2, v3 bitop3:0xf6
	s_add_i32 s21, s9, 0x18000
	s_or_b32 s65, s8, 0x80
	s_mov_b32 m0, s21
	s_add_i32 s64, s9, 0x1a000
	s_waitcnt vmcnt(2)
	s_barrier
	buffer_load_dwordx4 v131, s[36:39], s65 offen lds
	s_mov_b32 m0, s64
	s_or_b32 s78, s17, 0x80
	buffer_load_dwordx4 v133, s[36:39], s65 offen lds
	s_add_i32 s65, s9, 0x8000
	s_mov_b32 m0, s65
	s_add_i32 s67, s9, 0xa000
	buffer_load_dwordx4 v130, s[40:43], s78 offen lds
	s_mov_b32 m0, s67
	v_mov_b32_e32 v2, 0
	buffer_load_dwordx4 v132, s[40:43], s78 offen lds
	s_add_i32 s78, s9, 0x1c000
	s_or_b32 s43, s79, 0x80
	s_mov_b32 m0, s78
	s_add_i32 s79, s9, 0x1e000
	buffer_load_dwordx4 v131, s[36:39], s43 offen lds
	s_mov_b32 m0, s79
	v_lshl_or_b32 v218, s57, 6, v219
	buffer_load_dwordx4 v133, s[36:39], s43 offen lds
	s_waitcnt vmcnt(6)
	s_add_i32 s80, s9, 0xc000
	s_add_i32 s88, s9, 0xe000
	s_mov_b32 s89, -2
	s_mov_b32 s90, 0x160080
	v_add_u32_e32 v134, 0, v3
	v_add_u32_e32 v135, 0, v4
	v_mov_b32_e32 v3, v2
	v_mov_b32_e32 v4, v2
	v_mov_b32_e32 v5, v2
	v_mov_b32_e32 v6, v2
	v_mov_b32_e32 v7, v2
	v_mov_b32_e32 v8, v2
	v_mov_b32_e32 v9, v2
	v_mov_b32_e32 v22, v2
	v_mov_b32_e32 v23, v2
	v_mov_b32_e32 v24, v2
	v_mov_b32_e32 v25, v2
	v_mov_b32_e32 v30, v2
	v_mov_b32_e32 v31, v2
	v_mov_b32_e32 v32, v2
	v_mov_b32_e32 v33, v2
	v_mov_b32_e32 v110, v2
	v_mov_b32_e32 v111, v2
	v_mov_b32_e32 v112, v2
	v_mov_b32_e32 v113, v2
	v_mov_b32_e32 v122, v2
	v_mov_b32_e32 v123, v2
	v_mov_b32_e32 v124, v2
	v_mov_b32_e32 v125, v2
	v_mov_b32_e32 v118, v2
	v_mov_b32_e32 v119, v2
	v_mov_b32_e32 v120, v2
	v_mov_b32_e32 v121, v2
	v_mov_b32_e32 v126, v2
	v_mov_b32_e32 v127, v2
	v_mov_b32_e32 v128, v2
	v_mov_b32_e32 v129, v2
	v_mov_b32_e32 v10, v2
	v_mov_b32_e32 v11, v2
	v_mov_b32_e32 v12, v2
	v_mov_b32_e32 v13, v2
	v_mov_b32_e32 v14, v2
	v_mov_b32_e32 v15, v2
	v_mov_b32_e32 v16, v2
	v_mov_b32_e32 v17, v2
	v_mov_b32_e32 v66, v2
	v_mov_b32_e32 v67, v2
	v_mov_b32_e32 v68, v2
	v_mov_b32_e32 v69, v2
	v_mov_b32_e32 v74, v2
	v_mov_b32_e32 v75, v2
	v_mov_b32_e32 v76, v2
	v_mov_b32_e32 v77, v2
	v_mov_b32_e32 v106, v2
	v_mov_b32_e32 v107, v2
	v_mov_b32_e32 v108, v2
	v_mov_b32_e32 v109, v2
	v_mov_b32_e32 v114, v2
	v_mov_b32_e32 v115, v2
	v_mov_b32_e32 v116, v2
	v_mov_b32_e32 v117, v2
	v_mov_b32_e32 v90, v2
	v_mov_b32_e32 v91, v2
	v_mov_b32_e32 v92, v2
	v_mov_b32_e32 v93, v2
	v_mov_b32_e32 v94, v2
	v_mov_b32_e32 v95, v2
	v_mov_b32_e32 v96, v2
	v_mov_b32_e32 v97, v2
	v_mov_b32_e32 v98, v2
	v_mov_b32_e32 v99, v2
	v_mov_b32_e32 v100, v2
	v_mov_b32_e32 v101, v2
	v_mov_b32_e32 v102, v2
	v_mov_b32_e32 v103, v2
	v_mov_b32_e32 v104, v2
	v_mov_b32_e32 v105, v2
	v_mov_b32_e32 v82, v2
	v_mov_b32_e32 v83, v2
	v_mov_b32_e32 v84, v2
	v_mov_b32_e32 v85, v2
	v_mov_b32_e32 v86, v2
	v_mov_b32_e32 v87, v2
	v_mov_b32_e32 v88, v2
	v_mov_b32_e32 v89, v2
	v_mov_b32_e32 v58, v2
	v_mov_b32_e32 v59, v2
	v_mov_b32_e32 v60, v2
	v_mov_b32_e32 v61, v2
	v_mov_b32_e32 v62, v2
	v_mov_b32_e32 v63, v2
	v_mov_b32_e32 v64, v2
	v_mov_b32_e32 v65, v2
	v_mov_b32_e32 v38, v2
	v_mov_b32_e32 v39, v2
	v_mov_b32_e32 v40, v2
	v_mov_b32_e32 v41, v2
	v_mov_b32_e32 v46, v2
	v_mov_b32_e32 v47, v2
	v_mov_b32_e32 v48, v2
	v_mov_b32_e32 v49, v2
	v_mov_b32_e32 v70, v2
	v_mov_b32_e32 v71, v2
	v_mov_b32_e32 v72, v2
	v_mov_b32_e32 v73, v2
	v_mov_b32_e32 v78, v2
	v_mov_b32_e32 v79, v2
	v_mov_b32_e32 v80, v2
	v_mov_b32_e32 v81, v2
	v_mov_b32_e32 v50, v2
	v_mov_b32_e32 v51, v2
	v_mov_b32_e32 v52, v2
	v_mov_b32_e32 v53, v2
	v_mov_b32_e32 v54, v2
	v_mov_b32_e32 v55, v2
	v_mov_b32_e32 v56, v2
	v_mov_b32_e32 v57, v2
	v_mov_b32_e32 v34, v2
	v_mov_b32_e32 v35, v2
	v_mov_b32_e32 v36, v2
	v_mov_b32_e32 v37, v2
	v_mov_b32_e32 v42, v2
	v_mov_b32_e32 v43, v2
	v_mov_b32_e32 v44, v2
	v_mov_b32_e32 v45, v2
	v_mov_b32_e32 v18, v2
	v_mov_b32_e32 v19, v2
	v_mov_b32_e32 v20, v2
	v_mov_b32_e32 v21, v2
	v_mov_b32_e32 v26, v2
	v_mov_b32_e32 v27, v2
	v_mov_b32_e32 v28, v2
	v_mov_b32_e32 v29, v2
	s_barrier
	.p2align 3
.LBB0_366:
	v_add_u32_e32 v148, 0x10000, v134
	v_add_u32_e32 v164, 0x14000, v134
	ds_read_b128 v[136:139], v148
	ds_read_b128 v[140:143], v148 offset:1024
	ds_read_b128 v[144:147], v148 offset:2048
	ds_read_b128 v[148:151], v148 offset:3072
	ds_read_b128 v[152:155], v164
	ds_read_b128 v[156:159], v164 offset:1024
	ds_read_b128 v[160:163], v164 offset:2048
	ds_read_b128 v[164:167], v164 offset:3072
	s_add_i32 s39, s90, 0xffea0080
	s_cmpk_lg_i32 s89, 0x54
	s_cselect_b32 vcc_lo, s39, 0
	s_add_i32 vcc_hi, vcc_lo, s17
	s_nop 0
	s_or_b32 s91, vcc_hi, 0x80
	s_add_i32 s93, vcc_lo, s8
	s_add_i32 s39, s17, s90
	s_mov_b32 s43, s31
	s_mov_b32 m0, s80
	ds_read_b128 v[168:171], v135
	ds_read_b128 v[172:175], v135 offset:1024
	ds_read_b128 v[176:179], v135 offset:2048
	ds_read_b128 v[180:183], v135 offset:3072
	ds_read_b128 v[184:187], v135 offset:4096
	ds_read_b128 v[188:191], v135 offset:5120
	ds_read_b128 v[192:195], v135 offset:6144
	ds_read_b128 v[196:199], v135 offset:7168
	buffer_load_dwordx4 v130, s[40:43], s39 offen lds
	s_mov_b32 m0, s88
	s_nop 0
	buffer_load_dwordx4 v132, s[40:43], s39 offen lds
	s_waitcnt vmcnt(8)
	s_waitcnt lgkmcnt(0)
	s_barrier
	s_setprio 1
	s_waitcnt lgkmcnt(7)
	s_nop 0
	v_mfma_f32_16x16x32_bf16 v[26:29], v[136:139], v[168:171], v[26:29]
	v_mfma_f32_16x16x32_bf16 v[18:21], v[144:147], v[168:171], v[18:21]
	s_waitcnt lgkmcnt(5)
	s_nop 0
	v_mfma_f32_16x16x32_bf16 v[42:45], v[136:139], v[176:179], v[42:45]
	v_mfma_f32_16x16x32_bf16 v[34:37], v[144:147], v[176:179], v[34:37]
	s_waitcnt lgkmcnt(3)
	s_nop 0
	v_mfma_f32_16x16x32_bf16 v[54:57], v[136:139], v[184:187], v[54:57]
	v_mfma_f32_16x16x32_bf16 v[50:53], v[144:147], v[184:187], v[50:53]
	s_waitcnt lgkmcnt(1)
	s_nop 0
	v_mfma_f32_16x16x32_bf16 v[78:81], v[136:139], v[192:195], v[78:81]
	v_mfma_f32_16x16x32_bf16 v[70:73], v[144:147], v[192:195], v[70:73]
	v_mfma_f32_16x16x32_bf16 v[26:29], v[140:143], v[172:175], v[26:29]
	v_mfma_f32_16x16x32_bf16 v[18:21], v[148:151], v[172:175], v[18:21]
	v_mfma_f32_16x16x32_bf16 v[42:45], v[140:143], v[180:183], v[42:45]
	v_mfma_f32_16x16x32_bf16 v[34:37], v[148:151], v[180:183], v[34:37]
	v_mfma_f32_16x16x32_bf16 v[54:57], v[140:143], v[188:191], v[54:57]
	v_mfma_f32_16x16x32_bf16 v[50:53], v[148:151], v[188:191], v[50:53]
	s_waitcnt lgkmcnt(0)
	s_nop 0
	v_mfma_f32_16x16x32_bf16 v[78:81], v[140:143], v[196:199], v[78:81]
	v_mfma_f32_16x16x32_bf16 v[70:73], v[148:151], v[196:199], v[70:73]
	s_setprio 0
	s_setprio 1
	v_mfma_f32_16x16x32_bf16 v[46:49], v[152:155], v[168:171], v[46:49]
	v_mfma_f32_16x16x32_bf16 v[38:41], v[160:163], v[168:171], v[38:41]
	v_mfma_f32_16x16x32_bf16 v[62:65], v[152:155], v[176:179], v[62:65]
	v_mfma_f32_16x16x32_bf16 v[58:61], v[160:163], v[176:179], v[58:61]
	v_mfma_f32_16x16x32_bf16 v[86:89], v[152:155], v[184:187], v[86:89]
	v_mfma_f32_16x16x32_bf16 v[82:85], v[160:163], v[184:187], v[82:85]
	v_mfma_f32_16x16x32_bf16 v[102:105], v[152:155], v[192:195], v[102:105]
	v_mfma_f32_16x16x32_bf16 v[98:101], v[160:163], v[192:195], v[98:101]
	v_mfma_f32_16x16x32_bf16 v[46:49], v[156:159], v[172:175], v[46:49]
	v_mfma_f32_16x16x32_bf16 v[38:41], v[164:167], v[172:175], v[38:41]
	v_mfma_f32_16x16x32_bf16 v[62:65], v[156:159], v[180:183], v[62:65]
	v_mfma_f32_16x16x32_bf16 v[58:61], v[164:167], v[180:183], v[58:61]
	v_mfma_f32_16x16x32_bf16 v[86:89], v[156:159], v[188:191], v[86:89]
	v_mfma_f32_16x16x32_bf16 v[82:85], v[164:167], v[188:191], v[82:85]
	v_mfma_f32_16x16x32_bf16 v[102:105], v[156:159], v[196:199], v[102:105]
	v_mfma_f32_16x16x32_bf16 v[98:101], v[164:167], v[196:199], v[98:101]
	s_setprio 0
	s_barrier
	s_mov_b32 m0, s10
	s_mov_b32 s39, s31
	ds_read_b128 v[168:171], v135 offset:16384
	ds_read_b128 v[172:175], v135 offset:17408
	ds_read_b128 v[176:179], v135 offset:18432
	ds_read_b128 v[180:183], v135 offset:19456
	ds_read_b128 v[184:187], v135 offset:20480
	ds_read_b128 v[188:191], v135 offset:21504
	ds_read_b128 v[192:195], v135 offset:22528
	ds_read_b128 v[196:199], v135 offset:23552
	buffer_load_dwordx4 v131, s[36:39], s93 offen lds
	s_mov_b32 m0, s11
	s_nop 0
	s_add_i32 vcc_lo, s93, 0x160000
	buffer_load_dwordx4 v133, s[36:39], s93 offen lds
	s_mov_b32 m0, s15
	s_nop 0
	buffer_load_dwordx4 v131, s[36:39], vcc_lo offen lds
	s_mov_b32 m0, s16
	s_nop 0
	buffer_load_dwordx4 v133, s[36:39], vcc_lo offen lds
	s_mov_b32 m0, s9
	s_nop 0
	buffer_load_dwordx4 v130, s[40:43], vcc_hi offen lds
	s_mov_b32 m0, s18
	s_nop 0
	buffer_load_dwordx4 v132, s[40:43], vcc_hi offen lds
	s_waitcnt vmcnt(8)
	s_waitcnt lgkmcnt(0)
	s_barrier
	s_setprio 1
	s_waitcnt lgkmcnt(7)
	s_nop 0
	v_mfma_f32_16x16x32_bf16 v[94:97], v[136:139], v[168:171], v[94:97]
	v_mfma_f32_16x16x32_bf16 v[90:93], v[144:147], v[168:171], v[90:93]
	s_waitcnt lgkmcnt(5)
	s_nop 0
	v_mfma_f32_16x16x32_bf16 v[114:117], v[136:139], v[176:179], v[114:117]
	v_mfma_f32_16x16x32_bf16 v[106:109], v[144:147], v[176:179], v[106:109]
	s_waitcnt lgkmcnt(3)
	s_nop 0
	v_mfma_f32_16x16x32_bf16 v[74:77], v[136:139], v[184:187], v[74:77]
	v_mfma_f32_16x16x32_bf16 v[66:69], v[144:147], v[184:187], v[66:69]
	s_waitcnt lgkmcnt(1)
	s_nop 0
	v_mfma_f32_16x16x32_bf16 v[14:17], v[136:139], v[192:195], v[14:17]
	v_mfma_f32_16x16x32_bf16 v[10:13], v[144:147], v[192:195], v[10:13]
	v_mfma_f32_16x16x32_bf16 v[94:97], v[140:143], v[172:175], v[94:97]
	v_mfma_f32_16x16x32_bf16 v[90:93], v[148:151], v[172:175], v[90:93]
	v_mfma_f32_16x16x32_bf16 v[114:117], v[140:143], v[180:183], v[114:117]
	v_mfma_f32_16x16x32_bf16 v[106:109], v[148:151], v[180:183], v[106:109]
	v_mfma_f32_16x16x32_bf16 v[74:77], v[140:143], v[188:191], v[74:77]
	v_mfma_f32_16x16x32_bf16 v[66:69], v[148:151], v[188:191], v[66:69]
	s_waitcnt lgkmcnt(0)
	s_nop 0
	v_mfma_f32_16x16x32_bf16 v[14:17], v[140:143], v[196:199], v[14:17]
	v_mfma_f32_16x16x32_bf16 v[10:13], v[148:151], v[196:199], v[10:13]
	s_setprio 0
	s_setprio 1
	v_mfma_f32_16x16x32_bf16 v[126:129], v[152:155], v[168:171], v[126:129]
	v_mfma_f32_16x16x32_bf16 v[118:121], v[160:163], v[168:171], v[118:121]
	v_mfma_f32_16x16x32_bf16 v[122:125], v[152:155], v[176:179], v[122:125]
	v_mfma_f32_16x16x32_bf16 v[110:113], v[160:163], v[176:179], v[110:113]
	v_mfma_f32_16x16x32_bf16 v[30:33], v[152:155], v[184:187], v[30:33]
	v_mfma_f32_16x16x32_bf16 v[22:25], v[160:163], v[184:187], v[22:25]
	v_mfma_f32_16x16x32_bf16 v[6:9], v[152:155], v[192:195], v[6:9]
	v_mfma_f32_16x16x32_bf16 v[2:5], v[160:163], v[192:195], v[2:5]
	v_mfma_f32_16x16x32_bf16 v[126:129], v[156:159], v[172:175], v[126:129]
	v_mfma_f32_16x16x32_bf16 v[118:121], v[164:167], v[172:175], v[118:121]
	v_mfma_f32_16x16x32_bf16 v[122:125], v[156:159], v[180:183], v[122:125]
	v_mfma_f32_16x16x32_bf16 v[110:113], v[164:167], v[180:183], v[110:113]
	v_mfma_f32_16x16x32_bf16 v[30:33], v[156:159], v[188:191], v[30:33]
	v_mfma_f32_16x16x32_bf16 v[22:25], v[164:167], v[188:191], v[22:25]
	v_mfma_f32_16x16x32_bf16 v[6:9], v[156:159], v[196:199], v[6:9]
	v_mfma_f32_16x16x32_bf16 v[2:5], v[164:167], v[196:199], v[2:5]
	s_setprio 0
	s_barrier
	v_add_u32_e32 v148, 0x18000, v134
	v_add_u32_e32 v164, 0x1c000, v134
	ds_read_b128 v[136:139], v148
	ds_read_b128 v[140:143], v148 offset:1024
	ds_read_b128 v[144:147], v148 offset:2048
	ds_read_b128 v[148:151], v148 offset:3072
	ds_read_b128 v[152:155], v164
	ds_read_b128 v[156:159], v164 offset:1024
	ds_read_b128 v[160:163], v164 offset:2048
	ds_read_b128 v[164:167], v164 offset:3072
	s_add_i32 vcc_hi, vcc_hi, 0x160000
	s_mov_b32 m0, s19
	s_nop 0
	ds_read_b128 v[168:171], v135 offset:32768
	ds_read_b128 v[172:175], v135 offset:33792
	ds_read_b128 v[176:179], v135 offset:34816
	ds_read_b128 v[180:183], v135 offset:35840
	ds_read_b128 v[184:187], v135 offset:36864
	ds_read_b128 v[188:191], v135 offset:37888
	ds_read_b128 v[192:195], v135 offset:38912
	ds_read_b128 v[196:199], v135 offset:39936
	buffer_load_dwordx4 v130, s[40:43], vcc_hi offen lds
	s_mov_b32 m0, s20
	s_nop 0
	buffer_load_dwordx4 v132, s[40:43], vcc_hi offen lds
	s_waitcnt vmcnt(8)
	s_waitcnt lgkmcnt(0)
	s_barrier
	s_setprio 1
	s_waitcnt lgkmcnt(7)
	s_nop 0
	v_mfma_f32_16x16x32_bf16 v[26:29], v[136:139], v[168:171], v[26:29]
	v_mfma_f32_16x16x32_bf16 v[18:21], v[144:147], v[168:171], v[18:21]
	s_waitcnt lgkmcnt(5)
	s_nop 0
	v_mfma_f32_16x16x32_bf16 v[42:45], v[136:139], v[176:179], v[42:45]
	v_mfma_f32_16x16x32_bf16 v[34:37], v[144:147], v[176:179], v[34:37]
	s_waitcnt lgkmcnt(3)
	s_nop 0
	v_mfma_f32_16x16x32_bf16 v[54:57], v[136:139], v[184:187], v[54:57]
	v_mfma_f32_16x16x32_bf16 v[50:53], v[144:147], v[184:187], v[50:53]
	s_waitcnt lgkmcnt(1)
	s_nop 0
	v_mfma_f32_16x16x32_bf16 v[78:81], v[136:139], v[192:195], v[78:81]
	v_mfma_f32_16x16x32_bf16 v[70:73], v[144:147], v[192:195], v[70:73]
	v_mfma_f32_16x16x32_bf16 v[26:29], v[140:143], v[172:175], v[26:29]
	v_mfma_f32_16x16x32_bf16 v[18:21], v[148:151], v[172:175], v[18:21]
	v_mfma_f32_16x16x32_bf16 v[42:45], v[140:143], v[180:183], v[42:45]
	v_mfma_f32_16x16x32_bf16 v[34:37], v[148:151], v[180:183], v[34:37]
	v_mfma_f32_16x16x32_bf16 v[54:57], v[140:143], v[188:191], v[54:57]
	v_mfma_f32_16x16x32_bf16 v[50:53], v[148:151], v[188:191], v[50:53]
	s_waitcnt lgkmcnt(0)
	s_nop 0
	v_mfma_f32_16x16x32_bf16 v[78:81], v[140:143], v[196:199], v[78:81]
	v_mfma_f32_16x16x32_bf16 v[70:73], v[148:151], v[196:199], v[70:73]
	s_setprio 0
	s_setprio 1
	v_mfma_f32_16x16x32_bf16 v[46:49], v[152:155], v[168:171], v[46:49]
	v_mfma_f32_16x16x32_bf16 v[38:41], v[160:163], v[168:171], v[38:41]
	v_mfma_f32_16x16x32_bf16 v[62:65], v[152:155], v[176:179], v[62:65]
	v_mfma_f32_16x16x32_bf16 v[58:61], v[160:163], v[176:179], v[58:61]
	v_mfma_f32_16x16x32_bf16 v[86:89], v[152:155], v[184:187], v[86:89]
	v_mfma_f32_16x16x32_bf16 v[82:85], v[160:163], v[184:187], v[82:85]
	v_mfma_f32_16x16x32_bf16 v[102:105], v[152:155], v[192:195], v[102:105]
	v_mfma_f32_16x16x32_bf16 v[98:101], v[160:163], v[192:195], v[98:101]
	v_mfma_f32_16x16x32_bf16 v[46:49], v[156:159], v[172:175], v[46:49]
	v_mfma_f32_16x16x32_bf16 v[38:41], v[164:167], v[172:175], v[38:41]
	v_mfma_f32_16x16x32_bf16 v[62:65], v[156:159], v[180:183], v[62:65]
	v_mfma_f32_16x16x32_bf16 v[58:61], v[164:167], v[180:183], v[58:61]
	v_mfma_f32_16x16x32_bf16 v[86:89], v[156:159], v[188:191], v[86:89]
	v_mfma_f32_16x16x32_bf16 v[82:85], v[164:167], v[188:191], v[82:85]
	v_mfma_f32_16x16x32_bf16 v[102:105], v[156:159], v[196:199], v[102:105]
	v_mfma_f32_16x16x32_bf16 v[98:101], v[164:167], v[196:199], v[98:101]
	s_setprio 0
	s_barrier
	s_mov_b32 m0, s21
	s_nop 0
	s_or_b32 vcc_lo, s93, 0x80
	ds_read_b128 v[168:171], v135 offset:49152
	ds_read_b128 v[172:175], v135 offset:50176
	ds_read_b128 v[176:179], v135 offset:51200
	ds_read_b128 v[180:183], v135 offset:52224
	ds_read_b128 v[184:187], v135 offset:53248
	ds_read_b128 v[188:191], v135 offset:54272
	ds_read_b128 v[192:195], v135 offset:55296
	ds_read_b128 v[196:199], v135 offset:56320
	buffer_load_dwordx4 v131, s[36:39], vcc_lo offen lds
	s_mov_b32 m0, s64
	s_nop 0
	s_add_i32 s93, s93, 0x160080
	buffer_load_dwordx4 v133, s[36:39], vcc_lo offen lds
	s_mov_b32 m0, s78
	s_nop 0
	buffer_load_dwordx4 v131, s[36:39], s93 offen lds
	s_mov_b32 m0, s79
	s_nop 0
	buffer_load_dwordx4 v133, s[36:39], s93 offen lds
	s_mov_b32 m0, s65
	s_nop 0
	buffer_load_dwordx4 v130, s[40:43], s91 offen lds
	s_mov_b32 m0, s67
	s_nop 0
	buffer_load_dwordx4 v132, s[40:43], s91 offen lds
	s_waitcnt vmcnt(8)
	s_waitcnt lgkmcnt(0)
	s_barrier
	s_setprio 1
	s_waitcnt lgkmcnt(7)
	s_nop 0
	v_mfma_f32_16x16x32_bf16 v[94:97], v[136:139], v[168:171], v[94:97]
	v_mfma_f32_16x16x32_bf16 v[90:93], v[144:147], v[168:171], v[90:93]
	s_waitcnt lgkmcnt(5)
	s_nop 0
	v_mfma_f32_16x16x32_bf16 v[114:117], v[136:139], v[176:179], v[114:117]
	v_mfma_f32_16x16x32_bf16 v[106:109], v[144:147], v[176:179], v[106:109]
	s_waitcnt lgkmcnt(3)
	s_nop 0
	v_mfma_f32_16x16x32_bf16 v[74:77], v[136:139], v[184:187], v[74:77]
	v_mfma_f32_16x16x32_bf16 v[66:69], v[144:147], v[184:187], v[66:69]
	s_waitcnt lgkmcnt(1)
	s_nop 0
	v_mfma_f32_16x16x32_bf16 v[14:17], v[136:139], v[192:195], v[14:17]
	v_mfma_f32_16x16x32_bf16 v[10:13], v[144:147], v[192:195], v[10:13]
	v_mfma_f32_16x16x32_bf16 v[94:97], v[140:143], v[172:175], v[94:97]
	v_mfma_f32_16x16x32_bf16 v[90:93], v[148:151], v[172:175], v[90:93]
	v_mfma_f32_16x16x32_bf16 v[114:117], v[140:143], v[180:183], v[114:117]
	v_mfma_f32_16x16x32_bf16 v[106:109], v[148:151], v[180:183], v[106:109]
	v_mfma_f32_16x16x32_bf16 v[74:77], v[140:143], v[188:191], v[74:77]
	v_mfma_f32_16x16x32_bf16 v[66:69], v[148:151], v[188:191], v[66:69]
	s_waitcnt lgkmcnt(0)
	s_nop 0
	v_mfma_f32_16x16x32_bf16 v[14:17], v[140:143], v[196:199], v[14:17]
	v_mfma_f32_16x16x32_bf16 v[10:13], v[148:151], v[196:199], v[10:13]
	s_setprio 0
	s_setprio 1
	v_mfma_f32_16x16x32_bf16 v[126:129], v[152:155], v[168:171], v[126:129]
	v_mfma_f32_16x16x32_bf16 v[118:121], v[160:163], v[168:171], v[118:121]
	v_mfma_f32_16x16x32_bf16 v[122:125], v[152:155], v[176:179], v[122:125]
	v_mfma_f32_16x16x32_bf16 v[110:113], v[160:163], v[176:179], v[110:113]
	v_mfma_f32_16x16x32_bf16 v[30:33], v[152:155], v[184:187], v[30:33]
	v_mfma_f32_16x16x32_bf16 v[22:25], v[160:163], v[184:187], v[22:25]
	v_mfma_f32_16x16x32_bf16 v[6:9], v[152:155], v[192:195], v[6:9]
	v_mfma_f32_16x16x32_bf16 v[2:5], v[160:163], v[192:195], v[2:5]
	v_mfma_f32_16x16x32_bf16 v[126:129], v[156:159], v[172:175], v[126:129]
	v_mfma_f32_16x16x32_bf16 v[118:121], v[164:167], v[172:175], v[118:121]
	v_mfma_f32_16x16x32_bf16 v[122:125], v[156:159], v[180:183], v[122:125]
	v_mfma_f32_16x16x32_bf16 v[110:113], v[164:167], v[180:183], v[110:113]
	v_mfma_f32_16x16x32_bf16 v[30:33], v[156:159], v[188:191], v[30:33]
	v_mfma_f32_16x16x32_bf16 v[22:25], v[164:167], v[188:191], v[22:25]
	v_mfma_f32_16x16x32_bf16 v[6:9], v[156:159], v[196:199], v[6:9]
	v_mfma_f32_16x16x32_bf16 v[2:5], v[164:167], v[196:199], v[2:5]
	s_setprio 0
	s_barrier
	s_add_i32 s89, s89, 2
	s_addk_i32 s90, 0x100
	s_cmpk_lt_u32 s89, 0x56
	s_cbranch_scc1 .LBB0_366
	s_waitcnt vmcnt(0)
	s_cmpk_gt_u32 s66, 0xff
	s_cbranch_scc1 .LBB0_369
	s_barrier

.LBB0_815:
	s_lshl_b32 s12, s61, 20
	s_and_b64 s[64:65], s[4:5], exec
	s_cselect_b32 s64, s12, s66
	s_lshl_b32 s13, s60, 20
	s_and_b64 s[76:77], s[4:5], exec
	v_mov_b32_e32 v2, 0
	s_cselect_b32 s65, s13, s67
	s_add_i32 s66, s66, 0x80080
	s_addk_i32 s67, 0x100
	s_mov_b32 s76, -2
	v_mov_b32_e32 v3, v2
	v_mov_b32_e32 v4, v2
	v_mov_b32_e32 v5, v2
	v_mov_b32_e32 v6, v2
	v_mov_b32_e32 v7, v2
	v_mov_b32_e32 v8, v2
	v_mov_b32_e32 v9, v2
	v_mov_b32_e32 v10, v2
	v_mov_b32_e32 v11, v2
	v_mov_b32_e32 v12, v2
	v_mov_b32_e32 v13, v2
	v_mov_b32_e32 v18, v2
	v_mov_b32_e32 v19, v2
	v_mov_b32_e32 v20, v2
	v_mov_b32_e32 v21, v2
	v_mov_b32_e32 v26, v2
	v_mov_b32_e32 v27, v2
	v_mov_b32_e32 v28, v2
	v_mov_b32_e32 v29, v2
	v_mov_b32_e32 v34, v2
	v_mov_b32_e32 v35, v2
	v_mov_b32_e32 v36, v2
	v_mov_b32_e32 v37, v2
	v_mov_b32_e32 v42, v2
	v_mov_b32_e32 v43, v2
	v_mov_b32_e32 v44, v2
	v_mov_b32_e32 v45, v2
	v_mov_b32_e32 v50, v2
	v_mov_b32_e32 v51, v2
	v_mov_b32_e32 v52, v2
	v_mov_b32_e32 v53, v2
	v_mov_b32_e32 v14, v2
	v_mov_b32_e32 v15, v2
	v_mov_b32_e32 v16, v2
	v_mov_b32_e32 v17, v2
	v_mov_b32_e32 v22, v2
	v_mov_b32_e32 v23, v2
	v_mov_b32_e32 v24, v2
	v_mov_b32_e32 v25, v2
	v_mov_b32_e32 v30, v2
	v_mov_b32_e32 v31, v2
	v_mov_b32_e32 v32, v2
	v_mov_b32_e32 v33, v2
	v_mov_b32_e32 v38, v2
	v_mov_b32_e32 v39, v2
	v_mov_b32_e32 v40, v2
	v_mov_b32_e32 v41, v2
	v_mov_b32_e32 v46, v2
	v_mov_b32_e32 v47, v2
	v_mov_b32_e32 v48, v2
	v_mov_b32_e32 v49, v2
	v_mov_b32_e32 v54, v2
	v_mov_b32_e32 v55, v2
	v_mov_b32_e32 v56, v2
	v_mov_b32_e32 v57, v2
	v_mov_b32_e32 v58, v2
	v_mov_b32_e32 v59, v2
	v_mov_b32_e32 v60, v2
	v_mov_b32_e32 v61, v2
	v_mov_b32_e32 v62, v2
	v_mov_b32_e32 v63, v2
	v_mov_b32_e32 v64, v2
	v_mov_b32_e32 v65, v2
	v_mov_b32_e32 v66, v2
	v_mov_b32_e32 v67, v2
	v_mov_b32_e32 v68, v2
	v_mov_b32_e32 v69, v2
	v_mov_b32_e32 v70, v2
	v_mov_b32_e32 v71, v2
	v_mov_b32_e32 v72, v2
	v_mov_b32_e32 v73, v2
	v_mov_b32_e32 v74, v2
	v_mov_b32_e32 v75, v2
	v_mov_b32_e32 v76, v2
	v_mov_b32_e32 v77, v2
	v_mov_b32_e32 v82, v2
	v_mov_b32_e32 v83, v2
	v_mov_b32_e32 v84, v2
	v_mov_b32_e32 v85, v2
	v_mov_b32_e32 v90, v2
	v_mov_b32_e32 v91, v2
	v_mov_b32_e32 v92, v2
	v_mov_b32_e32 v93, v2
	v_mov_b32_e32 v98, v2
	v_mov_b32_e32 v99, v2
	v_mov_b32_e32 v100, v2
	v_mov_b32_e32 v101, v2
	v_mov_b32_e32 v106, v2
	v_mov_b32_e32 v107, v2
	v_mov_b32_e32 v108, v2
	v_mov_b32_e32 v109, v2
	v_mov_b32_e32 v114, v2
	v_mov_b32_e32 v115, v2
	v_mov_b32_e32 v116, v2
	v_mov_b32_e32 v117, v2
	v_mov_b32_e32 v78, v2
	v_mov_b32_e32 v79, v2
	v_mov_b32_e32 v80, v2
	v_mov_b32_e32 v81, v2
	v_mov_b32_e32 v86, v2
	v_mov_b32_e32 v87, v2
	v_mov_b32_e32 v88, v2
	v_mov_b32_e32 v89, v2
	v_mov_b32_e32 v94, v2
	v_mov_b32_e32 v95, v2
	v_mov_b32_e32 v96, v2
	v_mov_b32_e32 v97, v2
	v_mov_b32_e32 v102, v2
	v_mov_b32_e32 v103, v2
	v_mov_b32_e32 v104, v2
	v_mov_b32_e32 v105, v2
	v_mov_b32_e32 v110, v2
	v_mov_b32_e32 v111, v2
	v_mov_b32_e32 v112, v2
	v_mov_b32_e32 v113, v2
	v_mov_b32_e32 v118, v2
	v_mov_b32_e32 v119, v2
	v_mov_b32_e32 v120, v2
	v_mov_b32_e32 v121, v2
	v_mov_b32_e32 v122, v2
	v_mov_b32_e32 v123, v2
	v_mov_b32_e32 v124, v2
	v_mov_b32_e32 v125, v2
	v_mov_b32_e32 v126, v2
	v_mov_b32_e32 v127, v2
	v_mov_b32_e32 v128, v2
	v_mov_b32_e32 v129, v2
	.p2align 3
.LBB0_816:
	v_add_u32_e32 v157, 0x10000, v155
	ds_read_b128 v[134:137], v157
	ds_read_b128 v[158:161], v157 offset:1024
	ds_read_b128 v[162:165], v157 offset:2048
	ds_read_b128 v[166:169], v157 offset:3072
	v_add_u32_e32 v157, 0x14000, v155
	ds_read_b128 v[170:173], v157
	ds_read_b128 v[174:177], v157 offset:1024
	ds_read_b128 v[178:181], v157 offset:2048
	ds_read_b128 v[182:185], v157 offset:3072
	s_add_i32 s47, s66, 0xfff80080
	s_cmp_eq_u32 s76, 28
	s_cselect_b32 s79, s64, s47
	s_cselect_b32 s78, s65, s67
	s_nop 0
	s_or_b32 s77, s79, 0x80
	s_mov_b32 s47, s31
	s_mov_b32 m0, s53
	ds_read_b128 v[186:189], v156
	ds_read_b128 v[190:193], v156 offset:1024
	ds_read_b128 v[194:197], v156 offset:2048
	ds_read_b128 v[198:201], v156 offset:3072
	ds_read_b128 v[202:205], v156 offset:4096
	ds_read_b128 v[206:209], v156 offset:5120
	ds_read_b128 v[210:213], v156 offset:6144
	ds_read_b128 v[214:217], v156 offset:7168
	buffer_load_dwordx4 v131, s[44:47], s66 offen lds
	s_mov_b32 m0, s56
	s_nop 0
	buffer_load_dwordx4 v150, s[44:47], s66 offen lds
	s_waitcnt vmcnt(8)
	s_waitcnt lgkmcnt(0)
	s_barrier
	s_setprio 1
	s_waitcnt lgkmcnt(7)
	s_nop 0
	v_mfma_f32_16x16x32_bf16 v[126:129], v[134:137], v[186:189], v[126:129]
	v_mfma_f32_16x16x32_bf16 v[122:125], v[162:165], v[186:189], v[122:125]
	s_waitcnt lgkmcnt(5)
	s_nop 0
	v_mfma_f32_16x16x32_bf16 v[118:121], v[134:137], v[194:197], v[118:121]
	v_mfma_f32_16x16x32_bf16 v[110:113], v[162:165], v[194:197], v[110:113]
	s_waitcnt lgkmcnt(3)
	s_nop 0
	v_mfma_f32_16x16x32_bf16 v[102:105], v[134:137], v[202:205], v[102:105]
	v_mfma_f32_16x16x32_bf16 v[94:97], v[162:165], v[202:205], v[94:97]
	s_waitcnt lgkmcnt(1)
	s_nop 0
	v_mfma_f32_16x16x32_bf16 v[86:89], v[134:137], v[210:213], v[86:89]
	v_mfma_f32_16x16x32_bf16 v[78:81], v[162:165], v[210:213], v[78:81]
	v_mfma_f32_16x16x32_bf16 v[126:129], v[158:161], v[190:193], v[126:129]
	v_mfma_f32_16x16x32_bf16 v[122:125], v[166:169], v[190:193], v[122:125]
	v_mfma_f32_16x16x32_bf16 v[118:121], v[158:161], v[198:201], v[118:121]
	v_mfma_f32_16x16x32_bf16 v[110:113], v[166:169], v[198:201], v[110:113]
	v_mfma_f32_16x16x32_bf16 v[102:105], v[158:161], v[206:209], v[102:105]
	v_mfma_f32_16x16x32_bf16 v[94:97], v[166:169], v[206:209], v[94:97]
	s_waitcnt lgkmcnt(0)
	s_nop 0
	v_mfma_f32_16x16x32_bf16 v[86:89], v[158:161], v[214:217], v[86:89]
	v_mfma_f32_16x16x32_bf16 v[78:81], v[166:169], v[214:217], v[78:81]
	s_setprio 0
	s_setprio 1
	v_mfma_f32_16x16x32_bf16 v[114:117], v[170:173], v[186:189], v[114:117]
	v_mfma_f32_16x16x32_bf16 v[106:109], v[178:181], v[186:189], v[106:109]
	v_mfma_f32_16x16x32_bf16 v[98:101], v[170:173], v[194:197], v[98:101]
	v_mfma_f32_16x16x32_bf16 v[90:93], v[178:181], v[194:197], v[90:93]
	v_mfma_f32_16x16x32_bf16 v[82:85], v[170:173], v[202:205], v[82:85]
	v_mfma_f32_16x16x32_bf16 v[74:77], v[178:181], v[202:205], v[74:77]
	v_mfma_f32_16x16x32_bf16 v[70:73], v[170:173], v[210:213], v[70:73]
	v_mfma_f32_16x16x32_bf16 v[66:69], v[178:181], v[210:213], v[66:69]
	v_mfma_f32_16x16x32_bf16 v[114:117], v[174:177], v[190:193], v[114:117]
	v_mfma_f32_16x16x32_bf16 v[106:109], v[182:185], v[190:193], v[106:109]
	v_mfma_f32_16x16x32_bf16 v[98:101], v[174:177], v[198:201], v[98:101]
	v_mfma_f32_16x16x32_bf16 v[90:93], v[182:185], v[198:201], v[90:93]
	v_mfma_f32_16x16x32_bf16 v[82:85], v[174:177], v[206:209], v[82:85]
	v_mfma_f32_16x16x32_bf16 v[74:77], v[182:185], v[206:209], v[74:77]
	v_mfma_f32_16x16x32_bf16 v[70:73], v[174:177], v[214:217], v[70:73]
	v_mfma_f32_16x16x32_bf16 v[66:69], v[182:185], v[214:217], v[66:69]
	s_setprio 0
	s_barrier
	s_mov_b32 m0, s18
	s_mov_b32 s51, s31
	ds_read_b128 v[186:189], v156 offset:16384
	ds_read_b128 v[190:193], v156 offset:17408
	ds_read_b128 v[194:197], v156 offset:18432
	ds_read_b128 v[198:201], v156 offset:19456
	ds_read_b128 v[202:205], v156 offset:20480
	ds_read_b128 v[206:209], v156 offset:21504
	ds_read_b128 v[210:213], v156 offset:22528
	ds_read_b128 v[214:217], v156 offset:23552
	buffer_load_dwordx4 v149, s[48:51], s78 offen lds
	s_mov_b32 m0, s19
	s_nop 0
	s_add_i32 s80, s78, 0x80000
	buffer_load_dwordx4 v151, s[48:51], s78 offen lds
	s_mov_b32 m0, s22
	s_nop 0
	buffer_load_dwordx4 v149, s[48:51], s80 offen lds
	s_mov_b32 m0, s23
	s_nop 0
	buffer_load_dwordx4 v151, s[48:51], s80 offen lds
	s_mov_b32 m0, s17
	s_nop 0
	buffer_load_dwordx4 v131, s[44:47], s79 offen lds
	s_mov_b32 m0, s28
	s_nop 0
	buffer_load_dwordx4 v150, s[44:47], s79 offen lds
	s_waitcnt vmcnt(8)
	s_waitcnt lgkmcnt(0)
	s_barrier
	s_setprio 1
	s_waitcnt lgkmcnt(7)
	s_nop 0
	v_mfma_f32_16x16x32_bf16 v[62:65], v[134:137], v[186:189], v[62:65]
	v_mfma_f32_16x16x32_bf16 v[58:61], v[162:165], v[186:189], v[58:61]
	s_waitcnt lgkmcnt(5)
	s_nop 0
	v_mfma_f32_16x16x32_bf16 v[54:57], v[134:137], v[194:197], v[54:57]
	v_mfma_f32_16x16x32_bf16 v[46:49], v[162:165], v[194:197], v[46:49]
	s_waitcnt lgkmcnt(3)
	s_nop 0
	v_mfma_f32_16x16x32_bf16 v[38:41], v[134:137], v[202:205], v[38:41]
	v_mfma_f32_16x16x32_bf16 v[30:33], v[162:165], v[202:205], v[30:33]
	s_waitcnt lgkmcnt(1)
	s_nop 0
	v_mfma_f32_16x16x32_bf16 v[22:25], v[134:137], v[210:213], v[22:25]
	v_mfma_f32_16x16x32_bf16 v[14:17], v[162:165], v[210:213], v[14:17]
	v_mfma_f32_16x16x32_bf16 v[62:65], v[158:161], v[190:193], v[62:65]
	v_mfma_f32_16x16x32_bf16 v[58:61], v[166:169], v[190:193], v[58:61]
	v_mfma_f32_16x16x32_bf16 v[54:57], v[158:161], v[198:201], v[54:57]
	v_mfma_f32_16x16x32_bf16 v[46:49], v[166:169], v[198:201], v[46:49]
	v_mfma_f32_16x16x32_bf16 v[38:41], v[158:161], v[206:209], v[38:41]
	v_mfma_f32_16x16x32_bf16 v[30:33], v[166:169], v[206:209], v[30:33]
	s_waitcnt lgkmcnt(0)
	s_nop 0
	v_mfma_f32_16x16x32_bf16 v[22:25], v[158:161], v[214:217], v[22:25]
	v_mfma_f32_16x16x32_bf16 v[14:17], v[166:169], v[214:217], v[14:17]
	s_setprio 0
	s_setprio 1
	v_mfma_f32_16x16x32_bf16 v[50:53], v[170:173], v[186:189], v[50:53]
	v_mfma_f32_16x16x32_bf16 v[42:45], v[178:181], v[186:189], v[42:45]
	v_mfma_f32_16x16x32_bf16 v[34:37], v[170:173], v[194:197], v[34:37]
	v_mfma_f32_16x16x32_bf16 v[26:29], v[178:181], v[194:197], v[26:29]
	v_mfma_f32_16x16x32_bf16 v[18:21], v[170:173], v[202:205], v[18:21]
	v_mfma_f32_16x16x32_bf16 v[10:13], v[178:181], v[202:205], v[10:13]
	v_mfma_f32_16x16x32_bf16 v[6:9], v[170:173], v[210:213], v[6:9]
	v_mfma_f32_16x16x32_bf16 v[2:5], v[178:181], v[210:213], v[2:5]
	v_mfma_f32_16x16x32_bf16 v[50:53], v[174:177], v[190:193], v[50:53]
	v_mfma_f32_16x16x32_bf16 v[42:45], v[182:185], v[190:193], v[42:45]
	v_mfma_f32_16x16x32_bf16 v[34:37], v[174:177], v[198:201], v[34:37]
	v_mfma_f32_16x16x32_bf16 v[26:29], v[182:185], v[198:201], v[26:29]
	v_mfma_f32_16x16x32_bf16 v[18:21], v[174:177], v[206:209], v[18:21]
	v_mfma_f32_16x16x32_bf16 v[10:13], v[182:185], v[206:209], v[10:13]
	v_mfma_f32_16x16x32_bf16 v[6:9], v[174:177], v[214:217], v[6:9]
	v_mfma_f32_16x16x32_bf16 v[2:5], v[182:185], v[214:217], v[2:5]
	s_setprio 0
	s_barrier
	v_add_u32_e32 v157, 0x18000, v155
	ds_read_b128 v[134:137], v157
	ds_read_b128 v[158:161], v157 offset:1024
	ds_read_b128 v[162:165], v157 offset:2048
	ds_read_b128 v[166:169], v157 offset:3072
	v_add_u32_e32 v157, 0x1c000, v155
	ds_read_b128 v[170:173], v157
	ds_read_b128 v[174:177], v157 offset:1024
	ds_read_b128 v[178:181], v157 offset:2048
	ds_read_b128 v[182:185], v157 offset:3072
	s_add_i32 s79, s79, 0x80000
	s_mov_b32 m0, s29
	s_nop 0
	ds_read_b128 v[186:189], v156 offset:32768
	ds_read_b128 v[190:193], v156 offset:33792
	ds_read_b128 v[194:197], v156 offset:34816
	ds_read_b128 v[198:201], v156 offset:35840
	ds_read_b128 v[202:205], v156 offset:36864
	ds_read_b128 v[206:209], v156 offset:37888
	ds_read_b128 v[210:213], v156 offset:38912
	ds_read_b128 v[214:217], v156 offset:39936
	buffer_load_dwordx4 v131, s[44:47], s79 offen lds
	s_mov_b32 m0, s34
	s_nop 0
	buffer_load_dwordx4 v150, s[44:47], s79 offen lds
	s_waitcnt vmcnt(8)
	s_waitcnt lgkmcnt(0)
	s_barrier
	s_setprio 1
	s_waitcnt lgkmcnt(7)
	s_nop 0
	v_mfma_f32_16x16x32_bf16 v[126:129], v[134:137], v[186:189], v[126:129]
	v_mfma_f32_16x16x32_bf16 v[122:125], v[162:165], v[186:189], v[122:125]
	s_waitcnt lgkmcnt(5)
	s_nop 0
	v_mfma_f32_16x16x32_bf16 v[118:121], v[134:137], v[194:197], v[118:121]
	v_mfma_f32_16x16x32_bf16 v[110:113], v[162:165], v[194:197], v[110:113]
	s_waitcnt lgkmcnt(3)
	s_nop 0
	v_mfma_f32_16x16x32_bf16 v[102:105], v[134:137], v[202:205], v[102:105]
	v_mfma_f32_16x16x32_bf16 v[94:97], v[162:165], v[202:205], v[94:97]
	s_waitcnt lgkmcnt(1)
	s_nop 0
	v_mfma_f32_16x16x32_bf16 v[86:89], v[134:137], v[210:213], v[86:89]
	v_mfma_f32_16x16x32_bf16 v[78:81], v[162:165], v[210:213], v[78:81]
	v_mfma_f32_16x16x32_bf16 v[126:129], v[158:161], v[190:193], v[126:129]
	v_mfma_f32_16x16x32_bf16 v[122:125], v[166:169], v[190:193], v[122:125]
	v_mfma_f32_16x16x32_bf16 v[118:121], v[158:161], v[198:201], v[118:121]
	v_mfma_f32_16x16x32_bf16 v[110:113], v[166:169], v[198:201], v[110:113]
	v_mfma_f32_16x16x32_bf16 v[102:105], v[158:161], v[206:209], v[102:105]
	v_mfma_f32_16x16x32_bf16 v[94:97], v[166:169], v[206:209], v[94:97]
	s_waitcnt lgkmcnt(0)
	s_nop 0
	v_mfma_f32_16x16x32_bf16 v[86:89], v[158:161], v[214:217], v[86:89]
	v_mfma_f32_16x16x32_bf16 v[78:81], v[166:169], v[214:217], v[78:81]
	s_setprio 0
	s_setprio 1
	v_mfma_f32_16x16x32_bf16 v[114:117], v[170:173], v[186:189], v[114:117]
	v_mfma_f32_16x16x32_bf16 v[106:109], v[178:181], v[186:189], v[106:109]
	v_mfma_f32_16x16x32_bf16 v[98:101], v[170:173], v[194:197], v[98:101]
	v_mfma_f32_16x16x32_bf16 v[90:93], v[178:181], v[194:197], v[90:93]
	v_mfma_f32_16x16x32_bf16 v[82:85], v[170:173], v[202:205], v[82:85]
	v_mfma_f32_16x16x32_bf16 v[74:77], v[178:181], v[202:205], v[74:77]
	v_mfma_f32_16x16x32_bf16 v[70:73], v[170:173], v[210:213], v[70:73]
	v_mfma_f32_16x16x32_bf16 v[66:69], v[178:181], v[210:213], v[66:69]
	v_mfma_f32_16x16x32_bf16 v[114:117], v[174:177], v[190:193], v[114:117]
	v_mfma_f32_16x16x32_bf16 v[106:109], v[182:185], v[190:193], v[106:109]
	v_mfma_f32_16x16x32_bf16 v[98:101], v[174:177], v[198:201], v[98:101]
	v_mfma_f32_16x16x32_bf16 v[90:93], v[182:185], v[198:201], v[90:93]
	v_mfma_f32_16x16x32_bf16 v[82:85], v[174:177], v[206:209], v[82:85]
	v_mfma_f32_16x16x32_bf16 v[74:77], v[182:185], v[206:209], v[74:77]
	v_mfma_f32_16x16x32_bf16 v[70:73], v[174:177], v[214:217], v[70:73]
	v_mfma_f32_16x16x32_bf16 v[66:69], v[182:185], v[214:217], v[66:69]
	s_setprio 0
	s_barrier
	s_mov_b32 m0, s35
	s_nop 0
	s_or_b32 s79, s78, 0x80
	ds_read_b128 v[186:189], v156 offset:49152
	ds_read_b128 v[190:193], v156 offset:50176
	ds_read_b128 v[194:197], v156 offset:51200
	ds_read_b128 v[198:201], v156 offset:52224
	ds_read_b128 v[202:205], v156 offset:53248
	ds_read_b128 v[206:209], v156 offset:54272
	ds_read_b128 v[210:213], v156 offset:55296
	ds_read_b128 v[214:217], v156 offset:56320
	buffer_load_dwordx4 v149, s[48:51], s79 offen lds
	s_mov_b32 m0, s36
	s_nop 0
	s_add_i32 s78, s78, 0x80080
	buffer_load_dwordx4 v151, s[48:51], s79 offen lds
	s_mov_b32 m0, s41
	s_nop 0
	buffer_load_dwordx4 v149, s[48:51], s78 offen lds
	s_mov_b32 m0, s52
	s_nop 0
	buffer_load_dwordx4 v151, s[48:51], s78 offen lds
	s_mov_b32 m0, s37
	s_nop 0
	buffer_load_dwordx4 v131, s[44:47], s77 offen lds
	s_mov_b32 m0, s40
	s_nop 0
	buffer_load_dwordx4 v150, s[44:47], s77 offen lds
	s_waitcnt vmcnt(8)
	s_waitcnt lgkmcnt(0)
	s_barrier
	s_setprio 1
	s_waitcnt lgkmcnt(7)
	s_nop 0
	v_mfma_f32_16x16x32_bf16 v[62:65], v[134:137], v[186:189], v[62:65]
	v_mfma_f32_16x16x32_bf16 v[58:61], v[162:165], v[186:189], v[58:61]
	s_waitcnt lgkmcnt(5)
	s_nop 0
	v_mfma_f32_16x16x32_bf16 v[54:57], v[134:137], v[194:197], v[54:57]
	v_mfma_f32_16x16x32_bf16 v[46:49], v[162:165], v[194:197], v[46:49]
	s_waitcnt lgkmcnt(3)
	s_nop 0
	v_mfma_f32_16x16x32_bf16 v[38:41], v[134:137], v[202:205], v[38:41]
	v_mfma_f32_16x16x32_bf16 v[30:33], v[162:165], v[202:205], v[30:33]
	s_waitcnt lgkmcnt(1)
	s_nop 0
	v_mfma_f32_16x16x32_bf16 v[22:25], v[134:137], v[210:213], v[22:25]
	v_mfma_f32_16x16x32_bf16 v[14:17], v[162:165], v[210:213], v[14:17]
	v_mfma_f32_16x16x32_bf16 v[62:65], v[158:161], v[190:193], v[62:65]
	v_mfma_f32_16x16x32_bf16 v[58:61], v[166:169], v[190:193], v[58:61]
	v_mfma_f32_16x16x32_bf16 v[54:57], v[158:161], v[198:201], v[54:57]
	v_mfma_f32_16x16x32_bf16 v[46:49], v[166:169], v[198:201], v[46:49]
	v_mfma_f32_16x16x32_bf16 v[38:41], v[158:161], v[206:209], v[38:41]
	v_mfma_f32_16x16x32_bf16 v[30:33], v[166:169], v[206:209], v[30:33]
	s_waitcnt lgkmcnt(0)
	s_nop 0
	v_mfma_f32_16x16x32_bf16 v[22:25], v[158:161], v[214:217], v[22:25]
	v_mfma_f32_16x16x32_bf16 v[14:17], v[166:169], v[214:217], v[14:17]
	s_setprio 0
	s_setprio 1
	v_mfma_f32_16x16x32_bf16 v[50:53], v[170:173], v[186:189], v[50:53]
	v_mfma_f32_16x16x32_bf16 v[42:45], v[178:181], v[186:189], v[42:45]
	v_mfma_f32_16x16x32_bf16 v[34:37], v[170:173], v[194:197], v[34:37]
	v_mfma_f32_16x16x32_bf16 v[26:29], v[178:181], v[194:197], v[26:29]
	v_mfma_f32_16x16x32_bf16 v[18:21], v[170:173], v[202:205], v[18:21]
	v_mfma_f32_16x16x32_bf16 v[10:13], v[178:181], v[202:205], v[10:13]
	v_mfma_f32_16x16x32_bf16 v[6:9], v[170:173], v[210:213], v[6:9]
	v_mfma_f32_16x16x32_bf16 v[2:5], v[178:181], v[210:213], v[2:5]
	v_mfma_f32_16x16x32_bf16 v[50:53], v[174:177], v[190:193], v[50:53]
	v_mfma_f32_16x16x32_bf16 v[42:45], v[182:185], v[190:193], v[42:45]
	v_mfma_f32_16x16x32_bf16 v[34:37], v[174:177], v[198:201], v[34:37]
	v_mfma_f32_16x16x32_bf16 v[26:29], v[182:185], v[198:201], v[26:29]
	v_mfma_f32_16x16x32_bf16 v[18:21], v[174:177], v[206:209], v[18:21]
	v_mfma_f32_16x16x32_bf16 v[10:13], v[182:185], v[206:209], v[10:13]
	v_mfma_f32_16x16x32_bf16 v[6:9], v[174:177], v[214:217], v[6:9]
	v_mfma_f32_16x16x32_bf16 v[2:5], v[182:185], v[214:217], v[2:5]
	s_setprio 0
	s_barrier
	s_add_i32 s76, s76, 2
	s_addk_i32 s66, 0x100
	s_addk_i32 s67, 0x100
	s_cmp_gt_u32 s76, 29
	s_cbranch_scc0 .LBB0_816
	s_and_b64 vcc, exec, s[10:11]
	s_cbranch_vccz .LBB0_819
	s_barrier

.LBB0_843:
	s_lshl_b32 s14, s62, 19
	s_and_b64 s[66:67], s[6:7], exec
	s_cselect_b32 s66, s14, s76
	s_lshl_b32 s15, s17, 19
	s_and_b64 s[78:79], s[6:7], exec
	v_mov_b32_e32 v2, 0
	s_cselect_b32 s67, s15, s77
	s_add_i32 s76, s76, 0x40080
	s_addk_i32 s77, 0x100
	s_mov_b32 s78, -2
	v_mov_b32_e32 v3, v2
	v_mov_b32_e32 v4, v2
	v_mov_b32_e32 v5, v2
	v_mov_b32_e32 v6, v2
	v_mov_b32_e32 v7, v2
	v_mov_b32_e32 v8, v2
	v_mov_b32_e32 v9, v2
	v_mov_b32_e32 v18, v2
	v_mov_b32_e32 v19, v2
	v_mov_b32_e32 v20, v2
	v_mov_b32_e32 v21, v2
	v_mov_b32_e32 v22, v2
	v_mov_b32_e32 v23, v2
	v_mov_b32_e32 v24, v2
	v_mov_b32_e32 v25, v2
	v_mov_b32_e32 v34, v2
	v_mov_b32_e32 v35, v2
	v_mov_b32_e32 v36, v2
	v_mov_b32_e32 v37, v2
	v_mov_b32_e32 v38, v2
	v_mov_b32_e32 v39, v2
	v_mov_b32_e32 v40, v2
	v_mov_b32_e32 v41, v2
	v_mov_b32_e32 v50, v2
	v_mov_b32_e32 v51, v2
	v_mov_b32_e32 v52, v2
	v_mov_b32_e32 v53, v2
	v_mov_b32_e32 v54, v2
	v_mov_b32_e32 v55, v2
	v_mov_b32_e32 v56, v2
	v_mov_b32_e32 v57, v2
	v_mov_b32_e32 v10, v2
	v_mov_b32_e32 v11, v2
	v_mov_b32_e32 v12, v2
	v_mov_b32_e32 v13, v2
	v_mov_b32_e32 v14, v2
	v_mov_b32_e32 v15, v2
	v_mov_b32_e32 v16, v2
	v_mov_b32_e32 v17, v2
	v_mov_b32_e32 v26, v2
	v_mov_b32_e32 v27, v2
	v_mov_b32_e32 v28, v2
	v_mov_b32_e32 v29, v2
	v_mov_b32_e32 v30, v2
	v_mov_b32_e32 v31, v2
	v_mov_b32_e32 v32, v2
	v_mov_b32_e32 v33, v2
	v_mov_b32_e32 v42, v2
	v_mov_b32_e32 v43, v2
	v_mov_b32_e32 v44, v2
	v_mov_b32_e32 v45, v2
	v_mov_b32_e32 v46, v2
	v_mov_b32_e32 v47, v2
	v_mov_b32_e32 v48, v2
	v_mov_b32_e32 v49, v2
	v_mov_b32_e32 v58, v2
	v_mov_b32_e32 v59, v2
	v_mov_b32_e32 v60, v2
	v_mov_b32_e32 v61, v2
	v_mov_b32_e32 v62, v2
	v_mov_b32_e32 v63, v2
	v_mov_b32_e32 v64, v2
	v_mov_b32_e32 v65, v2
	v_mov_b32_e32 v66, v2
	v_mov_b32_e32 v67, v2
	v_mov_b32_e32 v68, v2
	v_mov_b32_e32 v69, v2
	v_mov_b32_e32 v70, v2
	v_mov_b32_e32 v71, v2
	v_mov_b32_e32 v72, v2
	v_mov_b32_e32 v73, v2
	v_mov_b32_e32 v82, v2
	v_mov_b32_e32 v83, v2
	v_mov_b32_e32 v84, v2
	v_mov_b32_e32 v85, v2
	v_mov_b32_e32 v86, v2
	v_mov_b32_e32 v87, v2
	v_mov_b32_e32 v88, v2
	v_mov_b32_e32 v89, v2
	v_mov_b32_e32 v98, v2
	v_mov_b32_e32 v99, v2
	v_mov_b32_e32 v100, v2
	v_mov_b32_e32 v101, v2
	v_mov_b32_e32 v102, v2
	v_mov_b32_e32 v103, v2
	v_mov_b32_e32 v104, v2
	v_mov_b32_e32 v105, v2
	v_mov_b32_e32 v114, v2
	v_mov_b32_e32 v115, v2
	v_mov_b32_e32 v116, v2
	v_mov_b32_e32 v117, v2
	v_mov_b32_e32 v118, v2
	v_mov_b32_e32 v119, v2
	v_mov_b32_e32 v120, v2
	v_mov_b32_e32 v121, v2
	v_mov_b32_e32 v74, v2
	v_mov_b32_e32 v75, v2
	v_mov_b32_e32 v76, v2
	v_mov_b32_e32 v77, v2
	v_mov_b32_e32 v78, v2
	v_mov_b32_e32 v79, v2
	v_mov_b32_e32 v80, v2
	v_mov_b32_e32 v81, v2
	v_mov_b32_e32 v90, v2
	v_mov_b32_e32 v91, v2
	v_mov_b32_e32 v92, v2
	v_mov_b32_e32 v93, v2
	v_mov_b32_e32 v94, v2
	v_mov_b32_e32 v95, v2
	v_mov_b32_e32 v96, v2
	v_mov_b32_e32 v97, v2
	v_mov_b32_e32 v106, v2
	v_mov_b32_e32 v107, v2
	v_mov_b32_e32 v108, v2
	v_mov_b32_e32 v109, v2
	v_mov_b32_e32 v110, v2
	v_mov_b32_e32 v111, v2
	v_mov_b32_e32 v112, v2
	v_mov_b32_e32 v113, v2
	v_mov_b32_e32 v138, v2
	v_mov_b32_e32 v139, v2
	v_mov_b32_e32 v140, v2
	v_mov_b32_e32 v141, v2
	v_mov_b32_e32 v142, v2
	v_mov_b32_e32 v143, v2
	v_mov_b32_e32 v144, v2
	v_mov_b32_e32 v145, v2
	.p2align 3
.LBB0_844:
	v_add_u32_e32 v134, 0x10000, v159
	v_add_u32_e32 v150, 0x14000, v159
	ds_read_b128 v[122:125], v134
	ds_read_b128 v[126:129], v134 offset:1024
	ds_read_b128 v[130:133], v134 offset:2048
	ds_read_b128 v[134:137], v134 offset:3072
	ds_read_b128 v[162:165], v150
	ds_read_b128 v[166:169], v150 offset:1024
	ds_read_b128 v[170:173], v150 offset:2048
	ds_read_b128 v[174:177], v150 offset:3072
	s_add_i32 s55, s76, 0xfffc0080
	s_cmp_eq_u32 s78, 12
	s_cselect_b32 s82, s66, s55
	s_cselect_b32 s80, s67, s77
	s_nop 0
	s_or_b32 s79, s82, 0x80
	s_mov_b32 m0, s59
	s_nop 0
	ds_read_b128 v[178:181], v160
	ds_read_b128 v[182:185], v160 offset:1024
	ds_read_b128 v[186:189], v160 offset:2048
	ds_read_b128 v[190:193], v160 offset:3072
	ds_read_b128 v[194:197], v160 offset:4096
	ds_read_b128 v[198:201], v160 offset:5120
	ds_read_b128 v[202:205], v160 offset:6144
	ds_read_b128 v[206:209], v160 offset:7168
	buffer_load_dwordx4 v153, s[28:31], s76 offen lds
	s_mov_b32 m0, s60
	s_nop 0
	buffer_load_dwordx4 v155, s[28:31], s76 offen lds
	s_waitcnt vmcnt(8)
	s_waitcnt lgkmcnt(0)
	s_barrier
	s_setprio 1
	s_waitcnt lgkmcnt(0)
	s_nop 0
	v_mfma_i32_16x16x64_i8 v[142:145], v[122:125], v[178:181], v[142:145]
	v_mfma_i32_16x16x64_i8 v[138:141], v[130:133], v[178:181], v[138:141]
	v_mfma_i32_16x16x64_i8 v[110:113], v[122:125], v[186:189], v[110:113]
	v_mfma_i32_16x16x64_i8 v[106:109], v[130:133], v[186:189], v[106:109]
	v_mfma_i32_16x16x64_i8 v[94:97], v[122:125], v[194:197], v[94:97]
	v_mfma_i32_16x16x64_i8 v[90:93], v[130:133], v[194:197], v[90:93]
	v_mfma_i32_16x16x64_i8 v[78:81], v[122:125], v[202:205], v[78:81]
	v_mfma_i32_16x16x64_i8 v[74:77], v[130:133], v[202:205], v[74:77]
	v_mfma_i32_16x16x64_i8 v[142:145], v[126:129], v[182:185], v[142:145]
	v_mfma_i32_16x16x64_i8 v[138:141], v[134:137], v[182:185], v[138:141]
	v_mfma_i32_16x16x64_i8 v[110:113], v[126:129], v[190:193], v[110:113]
	v_mfma_i32_16x16x64_i8 v[106:109], v[134:137], v[190:193], v[106:109]
	v_mfma_i32_16x16x64_i8 v[94:97], v[126:129], v[198:201], v[94:97]
	v_mfma_i32_16x16x64_i8 v[90:93], v[134:137], v[198:201], v[90:93]
	v_mfma_i32_16x16x64_i8 v[78:81], v[126:129], v[206:209], v[78:81]
	v_mfma_i32_16x16x64_i8 v[74:77], v[134:137], v[206:209], v[74:77]
	s_setprio 0
	s_setprio 1
	v_mfma_i32_16x16x64_i8 v[118:121], v[162:165], v[178:181], v[118:121]
	v_mfma_i32_16x16x64_i8 v[114:117], v[170:173], v[178:181], v[114:117]
	v_mfma_i32_16x16x64_i8 v[102:105], v[162:165], v[186:189], v[102:105]
	v_mfma_i32_16x16x64_i8 v[98:101], v[170:173], v[186:189], v[98:101]
	v_mfma_i32_16x16x64_i8 v[86:89], v[162:165], v[194:197], v[86:89]
	v_mfma_i32_16x16x64_i8 v[82:85], v[170:173], v[194:197], v[82:85]
	v_mfma_i32_16x16x64_i8 v[70:73], v[162:165], v[202:205], v[70:73]
	v_mfma_i32_16x16x64_i8 v[66:69], v[170:173], v[202:205], v[66:69]
	v_mfma_i32_16x16x64_i8 v[118:121], v[166:169], v[182:185], v[118:121]
	v_mfma_i32_16x16x64_i8 v[114:117], v[174:177], v[182:185], v[114:117]
	v_mfma_i32_16x16x64_i8 v[102:105], v[166:169], v[190:193], v[102:105]
	v_mfma_i32_16x16x64_i8 v[98:101], v[174:177], v[190:193], v[98:101]
	v_mfma_i32_16x16x64_i8 v[86:89], v[166:169], v[198:201], v[86:89]
	v_mfma_i32_16x16x64_i8 v[82:85], v[174:177], v[198:201], v[82:85]
	v_mfma_i32_16x16x64_i8 v[70:73], v[166:169], v[206:209], v[70:73]
	v_mfma_i32_16x16x64_i8 v[66:69], v[174:177], v[206:209], v[66:69]
	s_setprio 0
	s_barrier
	s_mov_b32 m0, s34
	s_mov_b32 s55, s31
	ds_read_b128 v[178:181], v160 offset:16384
	ds_read_b128 v[182:185], v160 offset:17408
	ds_read_b128 v[186:189], v160 offset:18432
	ds_read_b128 v[190:193], v160 offset:19456
	ds_read_b128 v[194:197], v160 offset:20480
	ds_read_b128 v[198:201], v160 offset:21504
	ds_read_b128 v[202:205], v160 offset:22528
	ds_read_b128 v[206:209], v160 offset:23552
	buffer_load_dwordx4 v154, s[52:55], s80 offen lds
	s_mov_b32 m0, s35
	s_nop 0
	s_add_i32 s83, s80, 0x40000
	buffer_load_dwordx4 v156, s[52:55], s80 offen lds
	s_mov_b32 m0, s36
	s_nop 0
	buffer_load_dwordx4 v154, s[52:55], s83 offen lds
	s_mov_b32 m0, s37
	s_nop 0
	buffer_load_dwordx4 v156, s[52:55], s83 offen lds
	s_mov_b32 m0, s23
	s_nop 0
	buffer_load_dwordx4 v153, s[28:31], s82 offen lds
	s_mov_b32 m0, s40
	s_nop 0
	buffer_load_dwordx4 v155, s[28:31], s82 offen lds
	s_waitcnt vmcnt(8)
	s_waitcnt lgkmcnt(0)
	s_barrier
	s_setprio 1
	s_waitcnt lgkmcnt(0)
	s_nop 0
	v_mfma_i32_16x16x64_i8 v[62:65], v[122:125], v[178:181], v[62:65]
	v_mfma_i32_16x16x64_i8 v[58:61], v[130:133], v[178:181], v[58:61]
	v_mfma_i32_16x16x64_i8 v[46:49], v[122:125], v[186:189], v[46:49]
	v_mfma_i32_16x16x64_i8 v[42:45], v[130:133], v[186:189], v[42:45]
	v_mfma_i32_16x16x64_i8 v[30:33], v[122:125], v[194:197], v[30:33]
	v_mfma_i32_16x16x64_i8 v[26:29], v[130:133], v[194:197], v[26:29]
	v_mfma_i32_16x16x64_i8 v[14:17], v[122:125], v[202:205], v[14:17]
	v_mfma_i32_16x16x64_i8 v[10:13], v[130:133], v[202:205], v[10:13]
	v_mfma_i32_16x16x64_i8 v[62:65], v[126:129], v[182:185], v[62:65]
	v_mfma_i32_16x16x64_i8 v[58:61], v[134:137], v[182:185], v[58:61]
	v_mfma_i32_16x16x64_i8 v[46:49], v[126:129], v[190:193], v[46:49]
	v_mfma_i32_16x16x64_i8 v[42:45], v[134:137], v[190:193], v[42:45]
	v_mfma_i32_16x16x64_i8 v[30:33], v[126:129], v[198:201], v[30:33]
	v_mfma_i32_16x16x64_i8 v[26:29], v[134:137], v[198:201], v[26:29]
	v_mfma_i32_16x16x64_i8 v[14:17], v[126:129], v[206:209], v[14:17]
	v_mfma_i32_16x16x64_i8 v[10:13], v[134:137], v[206:209], v[10:13]
	s_setprio 0
	s_setprio 1
	v_mfma_i32_16x16x64_i8 v[54:57], v[162:165], v[178:181], v[54:57]
	v_mfma_i32_16x16x64_i8 v[50:53], v[170:173], v[178:181], v[50:53]
	v_mfma_i32_16x16x64_i8 v[38:41], v[162:165], v[186:189], v[38:41]
	v_mfma_i32_16x16x64_i8 v[34:37], v[170:173], v[186:189], v[34:37]
	v_mfma_i32_16x16x64_i8 v[22:25], v[162:165], v[194:197], v[22:25]
	v_mfma_i32_16x16x64_i8 v[18:21], v[170:173], v[194:197], v[18:21]
	v_mfma_i32_16x16x64_i8 v[6:9], v[162:165], v[202:205], v[6:9]
	v_mfma_i32_16x16x64_i8 v[2:5], v[170:173], v[202:205], v[2:5]
	v_mfma_i32_16x16x64_i8 v[54:57], v[166:169], v[182:185], v[54:57]
	v_mfma_i32_16x16x64_i8 v[50:53], v[174:177], v[182:185], v[50:53]
	v_mfma_i32_16x16x64_i8 v[38:41], v[166:169], v[190:193], v[38:41]
	v_mfma_i32_16x16x64_i8 v[34:37], v[174:177], v[190:193], v[34:37]
	v_mfma_i32_16x16x64_i8 v[22:25], v[166:169], v[198:201], v[22:25]
	v_mfma_i32_16x16x64_i8 v[18:21], v[174:177], v[198:201], v[18:21]
	v_mfma_i32_16x16x64_i8 v[6:9], v[166:169], v[206:209], v[6:9]
	v_mfma_i32_16x16x64_i8 v[2:5], v[174:177], v[206:209], v[2:5]
	s_setprio 0
	s_barrier
	v_add_u32_e32 v134, 0x18000, v159
	v_add_u32_e32 v150, 0x1c000, v159
	ds_read_b128 v[122:125], v134
	ds_read_b128 v[126:129], v134 offset:1024
	ds_read_b128 v[130:133], v134 offset:2048
	ds_read_b128 v[134:137], v134 offset:3072
	ds_read_b128 v[162:165], v150
	ds_read_b128 v[166:169], v150 offset:1024
	ds_read_b128 v[170:173], v150 offset:2048
	ds_read_b128 v[174:177], v150 offset:3072
	s_add_i32 s82, s82, 0x40000
	s_mov_b32 m0, s41
	s_nop 0
	ds_read_b128 v[178:181], v160 offset:32768
	ds_read_b128 v[182:185], v160 offset:33792
	ds_read_b128 v[186:189], v160 offset:34816
	ds_read_b128 v[190:193], v160 offset:35840
	ds_read_b128 v[194:197], v160 offset:36864
	ds_read_b128 v[198:201], v160 offset:37888
	ds_read_b128 v[202:205], v160 offset:38912
	ds_read_b128 v[206:209], v160 offset:39936
	buffer_load_dwordx4 v153, s[28:31], s82 offen lds
	s_mov_b32 m0, s43
	s_nop 0
	buffer_load_dwordx4 v155, s[28:31], s82 offen lds
	s_waitcnt vmcnt(8)
	s_waitcnt lgkmcnt(0)
	s_barrier
	s_setprio 1
	s_waitcnt lgkmcnt(0)
	s_nop 0
	v_mfma_i32_16x16x64_i8 v[142:145], v[122:125], v[178:181], v[142:145]
	v_mfma_i32_16x16x64_i8 v[138:141], v[130:133], v[178:181], v[138:141]
	v_mfma_i32_16x16x64_i8 v[110:113], v[122:125], v[186:189], v[110:113]
	v_mfma_i32_16x16x64_i8 v[106:109], v[130:133], v[186:189], v[106:109]
	v_mfma_i32_16x16x64_i8 v[94:97], v[122:125], v[194:197], v[94:97]
	v_mfma_i32_16x16x64_i8 v[90:93], v[130:133], v[194:197], v[90:93]
	v_mfma_i32_16x16x64_i8 v[78:81], v[122:125], v[202:205], v[78:81]
	v_mfma_i32_16x16x64_i8 v[74:77], v[130:133], v[202:205], v[74:77]
	v_mfma_i32_16x16x64_i8 v[142:145], v[126:129], v[182:185], v[142:145]
	v_mfma_i32_16x16x64_i8 v[138:141], v[134:137], v[182:185], v[138:141]
	v_mfma_i32_16x16x64_i8 v[110:113], v[126:129], v[190:193], v[110:113]
	v_mfma_i32_16x16x64_i8 v[106:109], v[134:137], v[190:193], v[106:109]
	v_mfma_i32_16x16x64_i8 v[94:97], v[126:129], v[198:201], v[94:97]
	v_mfma_i32_16x16x64_i8 v[90:93], v[134:137], v[198:201], v[90:93]
	v_mfma_i32_16x16x64_i8 v[78:81], v[126:129], v[206:209], v[78:81]
	v_mfma_i32_16x16x64_i8 v[74:77], v[134:137], v[206:209], v[74:77]
	s_setprio 0
	s_setprio 1
	v_mfma_i32_16x16x64_i8 v[118:121], v[162:165], v[178:181], v[118:121]
	v_mfma_i32_16x16x64_i8 v[114:117], v[170:173], v[178:181], v[114:117]
	v_mfma_i32_16x16x64_i8 v[102:105], v[162:165], v[186:189], v[102:105]
	v_mfma_i32_16x16x64_i8 v[98:101], v[170:173], v[186:189], v[98:101]
	v_mfma_i32_16x16x64_i8 v[86:89], v[162:165], v[194:197], v[86:89]
	v_mfma_i32_16x16x64_i8 v[82:85], v[170:173], v[194:197], v[82:85]
	v_mfma_i32_16x16x64_i8 v[70:73], v[162:165], v[202:205], v[70:73]
	v_mfma_i32_16x16x64_i8 v[66:69], v[170:173], v[202:205], v[66:69]
	v_mfma_i32_16x16x64_i8 v[118:121], v[166:169], v[182:185], v[118:121]
	v_mfma_i32_16x16x64_i8 v[114:117], v[174:177], v[182:185], v[114:117]
	v_mfma_i32_16x16x64_i8 v[102:105], v[166:169], v[190:193], v[102:105]
	v_mfma_i32_16x16x64_i8 v[98:101], v[174:177], v[190:193], v[98:101]
	v_mfma_i32_16x16x64_i8 v[86:89], v[166:169], v[198:201], v[86:89]
	v_mfma_i32_16x16x64_i8 v[82:85], v[174:177], v[198:201], v[82:85]
	v_mfma_i32_16x16x64_i8 v[70:73], v[166:169], v[206:209], v[70:73]
	v_mfma_i32_16x16x64_i8 v[66:69], v[174:177], v[206:209], v[66:69]
	s_setprio 0
	s_barrier
	s_mov_b32 m0, s44
	s_nop 0
	s_or_b32 s82, s80, 0x80
	ds_read_b128 v[178:181], v160 offset:49152
	ds_read_b128 v[182:185], v160 offset:50176
	ds_read_b128 v[186:189], v160 offset:51200
	ds_read_b128 v[190:193], v160 offset:52224
	ds_read_b128 v[194:197], v160 offset:53248
	ds_read_b128 v[198:201], v160 offset:54272
	ds_read_b128 v[202:205], v160 offset:55296
	ds_read_b128 v[206:209], v160 offset:56320
	buffer_load_dwordx4 v154, s[52:55], s82 offen lds
	s_mov_b32 m0, s45
	s_nop 0
	s_add_i32 s80, s80, 0x40080
	buffer_load_dwordx4 v156, s[52:55], s82 offen lds
	s_mov_b32 m0, s49
	s_nop 0
	buffer_load_dwordx4 v154, s[52:55], s80 offen lds
	s_mov_b32 m0, s51
	s_nop 0
	buffer_load_dwordx4 v156, s[52:55], s80 offen lds
	s_mov_b32 m0, s47
	s_nop 0
	buffer_load_dwordx4 v153, s[28:31], s79 offen lds
	s_mov_b32 m0, s48
	s_nop 0
	buffer_load_dwordx4 v155, s[28:31], s79 offen lds
	s_waitcnt vmcnt(8)
	s_waitcnt lgkmcnt(0)
	s_barrier
	s_setprio 1
	s_waitcnt lgkmcnt(0)
	s_nop 0
	v_mfma_i32_16x16x64_i8 v[62:65], v[122:125], v[178:181], v[62:65]
	v_mfma_i32_16x16x64_i8 v[58:61], v[130:133], v[178:181], v[58:61]
	v_mfma_i32_16x16x64_i8 v[46:49], v[122:125], v[186:189], v[46:49]
	v_mfma_i32_16x16x64_i8 v[42:45], v[130:133], v[186:189], v[42:45]
	v_mfma_i32_16x16x64_i8 v[30:33], v[122:125], v[194:197], v[30:33]
	v_mfma_i32_16x16x64_i8 v[26:29], v[130:133], v[194:197], v[26:29]
	v_mfma_i32_16x16x64_i8 v[14:17], v[122:125], v[202:205], v[14:17]
	v_mfma_i32_16x16x64_i8 v[10:13], v[130:133], v[202:205], v[10:13]
	v_mfma_i32_16x16x64_i8 v[62:65], v[126:129], v[182:185], v[62:65]
	v_mfma_i32_16x16x64_i8 v[58:61], v[134:137], v[182:185], v[58:61]
	v_mfma_i32_16x16x64_i8 v[46:49], v[126:129], v[190:193], v[46:49]
	v_mfma_i32_16x16x64_i8 v[42:45], v[134:137], v[190:193], v[42:45]
	v_mfma_i32_16x16x64_i8 v[30:33], v[126:129], v[198:201], v[30:33]
	v_mfma_i32_16x16x64_i8 v[26:29], v[134:137], v[198:201], v[26:29]
	v_mfma_i32_16x16x64_i8 v[14:17], v[126:129], v[206:209], v[14:17]
	v_mfma_i32_16x16x64_i8 v[10:13], v[134:137], v[206:209], v[10:13]
	s_setprio 0
	s_setprio 1
	v_mfma_i32_16x16x64_i8 v[54:57], v[162:165], v[178:181], v[54:57]
	v_mfma_i32_16x16x64_i8 v[50:53], v[170:173], v[178:181], v[50:53]
	v_mfma_i32_16x16x64_i8 v[38:41], v[162:165], v[186:189], v[38:41]
	v_mfma_i32_16x16x64_i8 v[34:37], v[170:173], v[186:189], v[34:37]
	v_mfma_i32_16x16x64_i8 v[22:25], v[162:165], v[194:197], v[22:25]
	v_mfma_i32_16x16x64_i8 v[18:21], v[170:173], v[194:197], v[18:21]
	v_mfma_i32_16x16x64_i8 v[6:9], v[162:165], v[202:205], v[6:9]
	v_mfma_i32_16x16x64_i8 v[2:5], v[170:173], v[202:205], v[2:5]
	v_mfma_i32_16x16x64_i8 v[54:57], v[166:169], v[182:185], v[54:57]
	v_mfma_i32_16x16x64_i8 v[50:53], v[174:177], v[182:185], v[50:53]
	v_mfma_i32_16x16x64_i8 v[38:41], v[166:169], v[190:193], v[38:41]
	v_mfma_i32_16x16x64_i8 v[34:37], v[174:177], v[190:193], v[34:37]
	v_mfma_i32_16x16x64_i8 v[22:25], v[166:169], v[198:201], v[22:25]
	v_mfma_i32_16x16x64_i8 v[18:21], v[174:177], v[198:201], v[18:21]
	v_mfma_i32_16x16x64_i8 v[6:9], v[166:169], v[206:209], v[6:9]
	v_mfma_i32_16x16x64_i8 v[2:5], v[174:177], v[206:209], v[2:5]
	s_setprio 0
	s_barrier
	s_add_i32 s78, s78, 2
	s_addk_i32 s76, 0x100
	s_addk_i32 s77, 0x100
	s_cmp_gt_u32 s78, 13
	s_cbranch_scc0 .LBB0_844
	s_and_b64 vcc, exec, s[12:13]
	s_cbranch_vccz .LBB0_847
	s_barrier

.LBB0_1160:
	v_and_b32_e32 v219, 15, v210
	v_and_b32_e32 v2, 48, v210
	v_lshlrev_b32_e32 v3, 2, v210
	s_and_b32 s55, s10, 3
	s_lshl_b32 s19, s83, 13
	v_lshl_or_b32 v2, v219, 6, v2
	v_and_b32_e32 v3, 32, v3
	v_bitop3_b32 v4, v2, s19, v3 bitop3:0xde
	s_lshl_b32 s19, s55, 12
	v_bitop3_b32 v3, s19, v2, v3 bitop3:0xf6
	s_add_i32 s19, s7, 0x18000
	s_or_b32 s53, s6, 0x80
	s_mov_b32 m0, s19
	s_add_i32 s52, s7, 0x1a000
	s_waitcnt vmcnt(2)
	s_barrier
	buffer_load_dwordx4 v131, s[56:59], s53 offen lds
	s_mov_b32 m0, s52
	s_or_b32 s65, s15, 0x80
	buffer_load_dwordx4 v133, s[56:59], s53 offen lds
	s_add_i32 s53, s7, 0x8000
	s_mov_b32 m0, s53
	s_add_i32 s64, s7, 0xa000
	buffer_load_dwordx4 v130, s[44:47], s65 offen lds
	s_mov_b32 m0, s64
	s_add_i32 s76, s7, 0x1e000
	buffer_load_dwordx4 v132, s[44:47], s65 offen lds
	s_add_i32 s65, s7, 0x1c000
	s_or_b32 s47, s6, 0x80080
	s_mov_b32 m0, s65
	v_mov_b32_e32 v2, 0
	buffer_load_dwordx4 v131, s[56:59], s47 offen lds
	s_mov_b32 m0, s76
	v_lshl_or_b32 v218, s83, 6, v219
	buffer_load_dwordx4 v133, s[56:59], s47 offen lds
	s_waitcnt vmcnt(6)
	s_mov_b32 s67, 0x80080
	s_add_i32 s77, s7, 0xc000
	s_add_i32 s78, s7, 0xe000
	s_mov_b32 s79, -2
	v_add_u32_e32 v134, 0, v3
	v_add_u32_e32 v135, 0, v4
	v_mov_b32_e32 v3, v2
	v_mov_b32_e32 v4, v2
	v_mov_b32_e32 v5, v2
	v_mov_b32_e32 v6, v2
	v_mov_b32_e32 v7, v2
	v_mov_b32_e32 v8, v2
	v_mov_b32_e32 v9, v2
	v_mov_b32_e32 v18, v2
	v_mov_b32_e32 v19, v2
	v_mov_b32_e32 v20, v2
	v_mov_b32_e32 v21, v2
	v_mov_b32_e32 v22, v2
	v_mov_b32_e32 v23, v2
	v_mov_b32_e32 v24, v2
	v_mov_b32_e32 v25, v2
	v_mov_b32_e32 v62, v2
	v_mov_b32_e32 v63, v2
	v_mov_b32_e32 v64, v2
	v_mov_b32_e32 v65, v2
	v_mov_b32_e32 v70, v2
	v_mov_b32_e32 v71, v2
	v_mov_b32_e32 v72, v2
	v_mov_b32_e32 v73, v2
	v_mov_b32_e32 v114, v2
	v_mov_b32_e32 v115, v2
	v_mov_b32_e32 v116, v2
	v_mov_b32_e32 v117, v2
	v_mov_b32_e32 v122, v2
	v_mov_b32_e32 v123, v2
	v_mov_b32_e32 v124, v2
	v_mov_b32_e32 v125, v2
	v_mov_b32_e32 v10, v2
	v_mov_b32_e32 v11, v2
	v_mov_b32_e32 v12, v2
	v_mov_b32_e32 v13, v2
	v_mov_b32_e32 v14, v2
	v_mov_b32_e32 v15, v2
	v_mov_b32_e32 v16, v2
	v_mov_b32_e32 v17, v2
	v_mov_b32_e32 v38, v2
	v_mov_b32_e32 v39, v2
	v_mov_b32_e32 v40, v2
	v_mov_b32_e32 v41, v2
	v_mov_b32_e32 v46, v2
	v_mov_b32_e32 v47, v2
	v_mov_b32_e32 v48, v2
	v_mov_b32_e32 v49, v2
	v_mov_b32_e32 v90, v2
	v_mov_b32_e32 v91, v2
	v_mov_b32_e32 v92, v2
	v_mov_b32_e32 v93, v2
	v_mov_b32_e32 v98, v2
	v_mov_b32_e32 v99, v2
	v_mov_b32_e32 v100, v2
	v_mov_b32_e32 v101, v2
	v_mov_b32_e32 v118, v2
	v_mov_b32_e32 v119, v2
	v_mov_b32_e32 v120, v2
	v_mov_b32_e32 v121, v2
	v_mov_b32_e32 v126, v2
	v_mov_b32_e32 v127, v2
	v_mov_b32_e32 v128, v2
	v_mov_b32_e32 v129, v2
	v_mov_b32_e32 v106, v2
	v_mov_b32_e32 v107, v2
	v_mov_b32_e32 v108, v2
	v_mov_b32_e32 v109, v2
	v_mov_b32_e32 v110, v2
	v_mov_b32_e32 v111, v2
	v_mov_b32_e32 v112, v2
	v_mov_b32_e32 v113, v2
	v_mov_b32_e32 v82, v2
	v_mov_b32_e32 v83, v2
	v_mov_b32_e32 v84, v2
	v_mov_b32_e32 v85, v2
	v_mov_b32_e32 v86, v2
	v_mov_b32_e32 v87, v2
	v_mov_b32_e32 v88, v2
	v_mov_b32_e32 v89, v2
	v_mov_b32_e32 v58, v2
	v_mov_b32_e32 v59, v2
	v_mov_b32_e32 v60, v2
	v_mov_b32_e32 v61, v2
	v_mov_b32_e32 v66, v2
	v_mov_b32_e32 v67, v2
	v_mov_b32_e32 v68, v2
	v_mov_b32_e32 v69, v2
	v_mov_b32_e32 v34, v2
	v_mov_b32_e32 v35, v2
	v_mov_b32_e32 v36, v2
	v_mov_b32_e32 v37, v2
	v_mov_b32_e32 v42, v2
	v_mov_b32_e32 v43, v2
	v_mov_b32_e32 v44, v2
	v_mov_b32_e32 v45, v2
	v_mov_b32_e32 v94, v2
	v_mov_b32_e32 v95, v2
	v_mov_b32_e32 v96, v2
	v_mov_b32_e32 v97, v2
	v_mov_b32_e32 v102, v2
	v_mov_b32_e32 v103, v2
	v_mov_b32_e32 v104, v2
	v_mov_b32_e32 v105, v2
	v_mov_b32_e32 v74, v2
	v_mov_b32_e32 v75, v2
	v_mov_b32_e32 v76, v2
	v_mov_b32_e32 v77, v2
	v_mov_b32_e32 v78, v2
	v_mov_b32_e32 v79, v2
	v_mov_b32_e32 v80, v2
	v_mov_b32_e32 v81, v2
	v_mov_b32_e32 v50, v2
	v_mov_b32_e32 v51, v2
	v_mov_b32_e32 v52, v2
	v_mov_b32_e32 v53, v2
	v_mov_b32_e32 v54, v2
	v_mov_b32_e32 v55, v2
	v_mov_b32_e32 v56, v2
	v_mov_b32_e32 v57, v2
	v_mov_b32_e32 v26, v2
	v_mov_b32_e32 v27, v2
	v_mov_b32_e32 v28, v2
	v_mov_b32_e32 v29, v2
	v_mov_b32_e32 v30, v2
	v_mov_b32_e32 v31, v2
	v_mov_b32_e32 v32, v2
	v_mov_b32_e32 v33, v2
	s_barrier
	.p2align 3
.LBB0_1161:
	v_add_u32_e32 v148, 0x10000, v134
	v_add_u32_e32 v164, 0x14000, v134
	ds_read_b128 v[136:139], v148
	ds_read_b128 v[140:143], v148 offset:1024
	ds_read_b128 v[144:147], v148 offset:2048
	ds_read_b128 v[148:151], v148 offset:3072
	ds_read_b128 v[152:155], v164
	ds_read_b128 v[156:159], v164 offset:1024
	ds_read_b128 v[160:163], v164 offset:2048
	ds_read_b128 v[164:167], v164 offset:3072
	s_add_i32 s47, s67, 0xfff80080
	s_cmp_lg_u32 s79, 28
	s_cselect_b32 s88, s47, 0
	s_add_i32 s89, s88, s15
	s_nop 0
	s_or_b32 s80, s89, 0x80
	s_add_i32 s88, s88, s6
	s_add_i32 s59, s15, s67
	s_mov_b32 s47, s31
	s_mov_b32 m0, s77
	ds_read_b128 v[168:171], v135
	ds_read_b128 v[172:175], v135 offset:1024
	ds_read_b128 v[176:179], v135 offset:2048
	ds_read_b128 v[180:183], v135 offset:3072
	ds_read_b128 v[184:187], v135 offset:4096
	ds_read_b128 v[188:191], v135 offset:5120
	ds_read_b128 v[192:195], v135 offset:6144
	ds_read_b128 v[196:199], v135 offset:7168
	buffer_load_dwordx4 v130, s[44:47], s59 offen lds
	s_mov_b32 m0, s78
	s_nop 0
	buffer_load_dwordx4 v132, s[44:47], s59 offen lds
	s_waitcnt vmcnt(8)
	s_waitcnt lgkmcnt(0)
	s_barrier
	s_setprio 1
	s_waitcnt lgkmcnt(7)
	s_nop 0
	v_mfma_f32_16x16x32_bf16 v[30:33], v[136:139], v[168:171], v[30:33]
	v_mfma_f32_16x16x32_bf16 v[26:29], v[144:147], v[168:171], v[26:29]
	s_waitcnt lgkmcnt(5)
	s_nop 0
	v_mfma_f32_16x16x32_bf16 v[54:57], v[136:139], v[176:179], v[54:57]
	v_mfma_f32_16x16x32_bf16 v[50:53], v[144:147], v[176:179], v[50:53]
	s_waitcnt lgkmcnt(3)
	s_nop 0
	v_mfma_f32_16x16x32_bf16 v[78:81], v[136:139], v[184:187], v[78:81]
	v_mfma_f32_16x16x32_bf16 v[74:77], v[144:147], v[184:187], v[74:77]
	s_waitcnt lgkmcnt(1)
	s_nop 0
	v_mfma_f32_16x16x32_bf16 v[102:105], v[136:139], v[192:195], v[102:105]
	v_mfma_f32_16x16x32_bf16 v[94:97], v[144:147], v[192:195], v[94:97]
	v_mfma_f32_16x16x32_bf16 v[30:33], v[140:143], v[172:175], v[30:33]
	v_mfma_f32_16x16x32_bf16 v[26:29], v[148:151], v[172:175], v[26:29]
	v_mfma_f32_16x16x32_bf16 v[54:57], v[140:143], v[180:183], v[54:57]
	v_mfma_f32_16x16x32_bf16 v[50:53], v[148:151], v[180:183], v[50:53]
	v_mfma_f32_16x16x32_bf16 v[78:81], v[140:143], v[188:191], v[78:81]
	v_mfma_f32_16x16x32_bf16 v[74:77], v[148:151], v[188:191], v[74:77]
	s_waitcnt lgkmcnt(0)
	s_nop 0
	v_mfma_f32_16x16x32_bf16 v[102:105], v[140:143], v[196:199], v[102:105]
	v_mfma_f32_16x16x32_bf16 v[94:97], v[148:151], v[196:199], v[94:97]
	s_setprio 0
	s_setprio 1
	v_mfma_f32_16x16x32_bf16 v[42:45], v[152:155], v[168:171], v[42:45]
	v_mfma_f32_16x16x32_bf16 v[34:37], v[160:163], v[168:171], v[34:37]
	v_mfma_f32_16x16x32_bf16 v[66:69], v[152:155], v[176:179], v[66:69]
	v_mfma_f32_16x16x32_bf16 v[58:61], v[160:163], v[176:179], v[58:61]
	v_mfma_f32_16x16x32_bf16 v[86:89], v[152:155], v[184:187], v[86:89]
	v_mfma_f32_16x16x32_bf16 v[82:85], v[160:163], v[184:187], v[82:85]
	v_mfma_f32_16x16x32_bf16 v[110:113], v[152:155], v[192:195], v[110:113]
	v_mfma_f32_16x16x32_bf16 v[106:109], v[160:163], v[192:195], v[106:109]
	v_mfma_f32_16x16x32_bf16 v[42:45], v[156:159], v[172:175], v[42:45]
	v_mfma_f32_16x16x32_bf16 v[34:37], v[164:167], v[172:175], v[34:37]
	v_mfma_f32_16x16x32_bf16 v[66:69], v[156:159], v[180:183], v[66:69]
	v_mfma_f32_16x16x32_bf16 v[58:61], v[164:167], v[180:183], v[58:61]
	v_mfma_f32_16x16x32_bf16 v[86:89], v[156:159], v[188:191], v[86:89]
	v_mfma_f32_16x16x32_bf16 v[82:85], v[164:167], v[188:191], v[82:85]
	v_mfma_f32_16x16x32_bf16 v[110:113], v[156:159], v[196:199], v[110:113]
	v_mfma_f32_16x16x32_bf16 v[106:109], v[164:167], v[196:199], v[106:109]
	s_setprio 0
	s_barrier
	s_mov_b32 m0, s8
	s_mov_b32 s59, s31
	ds_read_b128 v[168:171], v135 offset:16384
	ds_read_b128 v[172:175], v135 offset:17408
	ds_read_b128 v[176:179], v135 offset:18432
	ds_read_b128 v[180:183], v135 offset:19456
	ds_read_b128 v[184:187], v135 offset:20480
	ds_read_b128 v[188:191], v135 offset:21504
	ds_read_b128 v[192:195], v135 offset:22528
	ds_read_b128 v[196:199], v135 offset:23552
	buffer_load_dwordx4 v131, s[56:59], s88 offen lds
	s_mov_b32 m0, s9
	s_nop 0
	s_add_i32 s90, s88, 0x80000
	buffer_load_dwordx4 v133, s[56:59], s88 offen lds
	s_mov_b32 m0, s13
	s_nop 0
	buffer_load_dwordx4 v131, s[56:59], s90 offen lds
	s_mov_b32 m0, s14
	s_nop 0
	buffer_load_dwordx4 v133, s[56:59], s90 offen lds
	s_mov_b32 m0, s7
	s_nop 0
	buffer_load_dwordx4 v130, s[44:47], s89 offen lds
	s_mov_b32 m0, s16
	s_nop 0
	buffer_load_dwordx4 v132, s[44:47], s89 offen lds
	s_waitcnt vmcnt(8)
	s_waitcnt lgkmcnt(0)
	s_barrier
	s_setprio 1
	s_waitcnt lgkmcnt(7)
	s_nop 0
	v_mfma_f32_16x16x32_bf16 v[126:129], v[136:139], v[168:171], v[126:129]
	v_mfma_f32_16x16x32_bf16 v[118:121], v[144:147], v[168:171], v[118:121]
	s_waitcnt lgkmcnt(5)
	s_nop 0
	v_mfma_f32_16x16x32_bf16 v[98:101], v[136:139], v[176:179], v[98:101]
	v_mfma_f32_16x16x32_bf16 v[90:93], v[144:147], v[176:179], v[90:93]
	s_waitcnt lgkmcnt(3)
	s_nop 0
	v_mfma_f32_16x16x32_bf16 v[46:49], v[136:139], v[184:187], v[46:49]
	v_mfma_f32_16x16x32_bf16 v[38:41], v[144:147], v[184:187], v[38:41]
	s_waitcnt lgkmcnt(1)
	s_nop 0
	v_mfma_f32_16x16x32_bf16 v[14:17], v[136:139], v[192:195], v[14:17]
	v_mfma_f32_16x16x32_bf16 v[10:13], v[144:147], v[192:195], v[10:13]
	v_mfma_f32_16x16x32_bf16 v[126:129], v[140:143], v[172:175], v[126:129]
	v_mfma_f32_16x16x32_bf16 v[118:121], v[148:151], v[172:175], v[118:121]
	v_mfma_f32_16x16x32_bf16 v[98:101], v[140:143], v[180:183], v[98:101]
	v_mfma_f32_16x16x32_bf16 v[90:93], v[148:151], v[180:183], v[90:93]
	v_mfma_f32_16x16x32_bf16 v[46:49], v[140:143], v[188:191], v[46:49]
	v_mfma_f32_16x16x32_bf16 v[38:41], v[148:151], v[188:191], v[38:41]
	s_waitcnt lgkmcnt(0)
	s_nop 0
	v_mfma_f32_16x16x32_bf16 v[14:17], v[140:143], v[196:199], v[14:17]
	v_mfma_f32_16x16x32_bf16 v[10:13], v[148:151], v[196:199], v[10:13]
	s_setprio 0
	s_setprio 1
	v_mfma_f32_16x16x32_bf16 v[122:125], v[152:155], v[168:171], v[122:125]
	v_mfma_f32_16x16x32_bf16 v[114:117], v[160:163], v[168:171], v[114:117]
	v_mfma_f32_16x16x32_bf16 v[70:73], v[152:155], v[176:179], v[70:73]
	v_mfma_f32_16x16x32_bf16 v[62:65], v[160:163], v[176:179], v[62:65]
	v_mfma_f32_16x16x32_bf16 v[22:25], v[152:155], v[184:187], v[22:25]
	v_mfma_f32_16x16x32_bf16 v[18:21], v[160:163], v[184:187], v[18:21]
	v_mfma_f32_16x16x32_bf16 v[6:9], v[152:155], v[192:195], v[6:9]
	v_mfma_f32_16x16x32_bf16 v[2:5], v[160:163], v[192:195], v[2:5]
	v_mfma_f32_16x16x32_bf16 v[122:125], v[156:159], v[172:175], v[122:125]
	v_mfma_f32_16x16x32_bf16 v[114:117], v[164:167], v[172:175], v[114:117]
	v_mfma_f32_16x16x32_bf16 v[70:73], v[156:159], v[180:183], v[70:73]
	v_mfma_f32_16x16x32_bf16 v[62:65], v[164:167], v[180:183], v[62:65]
	v_mfma_f32_16x16x32_bf16 v[22:25], v[156:159], v[188:191], v[22:25]
	v_mfma_f32_16x16x32_bf16 v[18:21], v[164:167], v[188:191], v[18:21]
	v_mfma_f32_16x16x32_bf16 v[6:9], v[156:159], v[196:199], v[6:9]
	v_mfma_f32_16x16x32_bf16 v[2:5], v[164:167], v[196:199], v[2:5]
	s_setprio 0
	s_barrier
	v_add_u32_e32 v148, 0x18000, v134
	v_add_u32_e32 v164, 0x1c000, v134
	ds_read_b128 v[136:139], v148
	ds_read_b128 v[140:143], v148 offset:1024
	ds_read_b128 v[144:147], v148 offset:2048
	ds_read_b128 v[148:151], v148 offset:3072
	ds_read_b128 v[152:155], v164
	ds_read_b128 v[156:159], v164 offset:1024
	ds_read_b128 v[160:163], v164 offset:2048
	ds_read_b128 v[164:167], v164 offset:3072
	s_add_i32 s89, s89, 0x80000
	s_mov_b32 m0, s17
	s_nop 0
	ds_read_b128 v[168:171], v135 offset:32768
	ds_read_b128 v[172:175], v135 offset:33792
	ds_read_b128 v[176:179], v135 offset:34816
	ds_read_b128 v[180:183], v135 offset:35840
	ds_read_b128 v[184:187], v135 offset:36864
	ds_read_b128 v[188:191], v135 offset:37888
	ds_read_b128 v[192:195], v135 offset:38912
	ds_read_b128 v[196:199], v135 offset:39936
	buffer_load_dwordx4 v130, s[44:47], s89 offen lds
	s_mov_b32 m0, s18
	s_nop 0
	buffer_load_dwordx4 v132, s[44:47], s89 offen lds
	s_waitcnt vmcnt(8)
	s_waitcnt lgkmcnt(0)
	s_barrier
	s_setprio 1
	s_waitcnt lgkmcnt(7)
	s_nop 0
	v_mfma_f32_16x16x32_bf16 v[30:33], v[136:139], v[168:171], v[30:33]
	v_mfma_f32_16x16x32_bf16 v[26:29], v[144:147], v[168:171], v[26:29]
	s_waitcnt lgkmcnt(5)
	s_nop 0
	v_mfma_f32_16x16x32_bf16 v[54:57], v[136:139], v[176:179], v[54:57]
	v_mfma_f32_16x16x32_bf16 v[50:53], v[144:147], v[176:179], v[50:53]
	s_waitcnt lgkmcnt(3)
	s_nop 0
	v_mfma_f32_16x16x32_bf16 v[78:81], v[136:139], v[184:187], v[78:81]
	v_mfma_f32_16x16x32_bf16 v[74:77], v[144:147], v[184:187], v[74:77]
	s_waitcnt lgkmcnt(1)
	s_nop 0
	v_mfma_f32_16x16x32_bf16 v[102:105], v[136:139], v[192:195], v[102:105]
	v_mfma_f32_16x16x32_bf16 v[94:97], v[144:147], v[192:195], v[94:97]
	v_mfma_f32_16x16x32_bf16 v[30:33], v[140:143], v[172:175], v[30:33]
	v_mfma_f32_16x16x32_bf16 v[26:29], v[148:151], v[172:175], v[26:29]
	v_mfma_f32_16x16x32_bf16 v[54:57], v[140:143], v[180:183], v[54:57]
	v_mfma_f32_16x16x32_bf16 v[50:53], v[148:151], v[180:183], v[50:53]
	v_mfma_f32_16x16x32_bf16 v[78:81], v[140:143], v[188:191], v[78:81]
	v_mfma_f32_16x16x32_bf16 v[74:77], v[148:151], v[188:191], v[74:77]
	s_waitcnt lgkmcnt(0)
	s_nop 0
	v_mfma_f32_16x16x32_bf16 v[102:105], v[140:143], v[196:199], v[102:105]
	v_mfma_f32_16x16x32_bf16 v[94:97], v[148:151], v[196:199], v[94:97]
	s_setprio 0
	s_setprio 1
	v_mfma_f32_16x16x32_bf16 v[42:45], v[152:155], v[168:171], v[42:45]
	v_mfma_f32_16x16x32_bf16 v[34:37], v[160:163], v[168:171], v[34:37]
	v_mfma_f32_16x16x32_bf16 v[66:69], v[152:155], v[176:179], v[66:69]
	v_mfma_f32_16x16x32_bf16 v[58:61], v[160:163], v[176:179], v[58:61]
	v_mfma_f32_16x16x32_bf16 v[86:89], v[152:155], v[184:187], v[86:89]
	v_mfma_f32_16x16x32_bf16 v[82:85], v[160:163], v[184:187], v[82:85]
	v_mfma_f32_16x16x32_bf16 v[110:113], v[152:155], v[192:195], v[110:113]
	v_mfma_f32_16x16x32_bf16 v[106:109], v[160:163], v[192:195], v[106:109]
	v_mfma_f32_16x16x32_bf16 v[42:45], v[156:159], v[172:175], v[42:45]
	v_mfma_f32_16x16x32_bf16 v[34:37], v[164:167], v[172:175], v[34:37]
	v_mfma_f32_16x16x32_bf16 v[66:69], v[156:159], v[180:183], v[66:69]
	v_mfma_f32_16x16x32_bf16 v[58:61], v[164:167], v[180:183], v[58:61]
	v_mfma_f32_16x16x32_bf16 v[86:89], v[156:159], v[188:191], v[86:89]
	v_mfma_f32_16x16x32_bf16 v[82:85], v[164:167], v[188:191], v[82:85]
	v_mfma_f32_16x16x32_bf16 v[110:113], v[156:159], v[196:199], v[110:113]
	v_mfma_f32_16x16x32_bf16 v[106:109], v[164:167], v[196:199], v[106:109]
	s_setprio 0
	s_barrier
	s_mov_b32 m0, s19
	s_nop 0
	s_or_b32 s89, s88, 0x80
	ds_read_b128 v[168:171], v135 offset:49152
	ds_read_b128 v[172:175], v135 offset:50176
	ds_read_b128 v[176:179], v135 offset:51200
	ds_read_b128 v[180:183], v135 offset:52224
	ds_read_b128 v[184:187], v135 offset:53248
	ds_read_b128 v[188:191], v135 offset:54272
	ds_read_b128 v[192:195], v135 offset:55296
	ds_read_b128 v[196:199], v135 offset:56320
	buffer_load_dwordx4 v131, s[56:59], s89 offen lds
	s_mov_b32 m0, s52
	s_nop 0
	s_add_i32 s88, s88, 0x80080
	buffer_load_dwordx4 v133, s[56:59], s89 offen lds
	s_mov_b32 m0, s65
	s_nop 0
	buffer_load_dwordx4 v131, s[56:59], s88 offen lds
	s_mov_b32 m0, s76
	s_nop 0
	buffer_load_dwordx4 v133, s[56:59], s88 offen lds
	s_mov_b32 m0, s53
	s_nop 0
	buffer_load_dwordx4 v130, s[44:47], s80 offen lds
	s_mov_b32 m0, s64
	s_nop 0
	buffer_load_dwordx4 v132, s[44:47], s80 offen lds
	s_waitcnt vmcnt(8)
	s_waitcnt lgkmcnt(0)
	s_barrier
	s_setprio 1
	s_waitcnt lgkmcnt(7)
	s_nop 0
	v_mfma_f32_16x16x32_bf16 v[126:129], v[136:139], v[168:171], v[126:129]
	v_mfma_f32_16x16x32_bf16 v[118:121], v[144:147], v[168:171], v[118:121]
	s_waitcnt lgkmcnt(5)
	s_nop 0
	v_mfma_f32_16x16x32_bf16 v[98:101], v[136:139], v[176:179], v[98:101]
	v_mfma_f32_16x16x32_bf16 v[90:93], v[144:147], v[176:179], v[90:93]
	s_waitcnt lgkmcnt(3)
	s_nop 0
	v_mfma_f32_16x16x32_bf16 v[46:49], v[136:139], v[184:187], v[46:49]
	v_mfma_f32_16x16x32_bf16 v[38:41], v[144:147], v[184:187], v[38:41]
	s_waitcnt lgkmcnt(1)
	s_nop 0
	v_mfma_f32_16x16x32_bf16 v[14:17], v[136:139], v[192:195], v[14:17]
	v_mfma_f32_16x16x32_bf16 v[10:13], v[144:147], v[192:195], v[10:13]
	v_mfma_f32_16x16x32_bf16 v[126:129], v[140:143], v[172:175], v[126:129]
	v_mfma_f32_16x16x32_bf16 v[118:121], v[148:151], v[172:175], v[118:121]
	v_mfma_f32_16x16x32_bf16 v[98:101], v[140:143], v[180:183], v[98:101]
	v_mfma_f32_16x16x32_bf16 v[90:93], v[148:151], v[180:183], v[90:93]
	v_mfma_f32_16x16x32_bf16 v[46:49], v[140:143], v[188:191], v[46:49]
	v_mfma_f32_16x16x32_bf16 v[38:41], v[148:151], v[188:191], v[38:41]
	s_waitcnt lgkmcnt(0)
	s_nop 0
	v_mfma_f32_16x16x32_bf16 v[14:17], v[140:143], v[196:199], v[14:17]
	v_mfma_f32_16x16x32_bf16 v[10:13], v[148:151], v[196:199], v[10:13]
	s_setprio 0
	s_setprio 1
	v_mfma_f32_16x16x32_bf16 v[122:125], v[152:155], v[168:171], v[122:125]
	v_mfma_f32_16x16x32_bf16 v[114:117], v[160:163], v[168:171], v[114:117]
	v_mfma_f32_16x16x32_bf16 v[70:73], v[152:155], v[176:179], v[70:73]
	v_mfma_f32_16x16x32_bf16 v[62:65], v[160:163], v[176:179], v[62:65]
	v_mfma_f32_16x16x32_bf16 v[22:25], v[152:155], v[184:187], v[22:25]
	v_mfma_f32_16x16x32_bf16 v[18:21], v[160:163], v[184:187], v[18:21]
	v_mfma_f32_16x16x32_bf16 v[6:9], v[152:155], v[192:195], v[6:9]
	v_mfma_f32_16x16x32_bf16 v[2:5], v[160:163], v[192:195], v[2:5]
	v_mfma_f32_16x16x32_bf16 v[122:125], v[156:159], v[172:175], v[122:125]
	v_mfma_f32_16x16x32_bf16 v[114:117], v[164:167], v[172:175], v[114:117]
	v_mfma_f32_16x16x32_bf16 v[70:73], v[156:159], v[180:183], v[70:73]
	v_mfma_f32_16x16x32_bf16 v[62:65], v[164:167], v[180:183], v[62:65]
	v_mfma_f32_16x16x32_bf16 v[22:25], v[156:159], v[188:191], v[22:25]
	v_mfma_f32_16x16x32_bf16 v[18:21], v[164:167], v[188:191], v[18:21]
	v_mfma_f32_16x16x32_bf16 v[6:9], v[156:159], v[196:199], v[6:9]
	v_mfma_f32_16x16x32_bf16 v[2:5], v[164:167], v[196:199], v[2:5]
	s_setprio 0
	s_barrier
	s_add_i32 s79, s79, 2
	s_addk_i32 s67, 0x100
	s_cmp_lt_u32 s79, 30
	s_cbranch_scc1 .LBB0_1161
	s_waitcnt vmcnt(0)
	s_cmpk_gt_u32 s66, 0xff
	s_cbranch_scc1 .LBB0_1164
	s_barrier
